# NA: quad-coalesced V loads with in-register dword rotation for conflict-free LDS transposition; 7 hoisted K loads; P3 rebalanced
# speedup vs baseline: 1.0747x; 1.0067x over previous
; __device__ __forceinline__ void na2_task(const Params& p_, int l, int task, unsigned char* lds) {
;     ...
;     { const int pair = lane & 31, chunk = (lane >> 5) + 2 * (w & 3);
;       unsigned* VTd = (unsigned*)(VT + (size_t)hh * 64 * 520);
;       u32x4 xs[8], ys[8];
; #pragma unroll
;       for (int a = 0; a < 8; ++a) { const size_t tok = (size_t)b * SEQ + (row_start + a) * 64 + 2 * pair;
;           const bf16* src = Z + tok * DIN + 4 * DG + h * 64 + chunk * 8; xs[a] = *(const u32x4*)src; ys[a] = *(const u32x4*)(src + DIN); }
;     ...
;             for (int i = 0; i < 8; ++i) { const int a = 4 + i / 2, ci = i % 2;
;                 const size_t ktok = (size_t)b * SEQ + (row_start + a) * 64 + kst + 16 * ci + fr;
; #pragma unroll
;                 for (int ks = 0; ks < 2; ++ks) kfr[i][ks] = *(const bf16x8v*)(Z + ktok * DIN + 3 * DG + h * 64 + 32 * ks + 8 * fq); }
.LBB0_385:
	v_bfe_u32 v172, v147, 2, 3
	v_bfe_u32 v249, v147, 6, 2
	v_lshl_or_b32 v172, v249, 3, v172
	v_lshl_or_b32 v88, v172, 1, s42
	v_or_b32_e32 v81, s24, v88
	v_mov_b64_e32 v[86:87], s[40:41]
	v_and_b32_e32 v173, 3, v147
	v_bfe_u32 v249, v147, 5, 1
	v_lshl_or_b32 v173, v249, 2, v173
	v_lshlrev_b32_e32 v173, 3, v173
	v_mad_u64_u32 v[94:95], s[40:41], v81, s75, v[86:87]
	v_mad_i32_i24 v95, s43, v195, v95
	v_mov_b32_e32 v89, s43
	v_lshl_add_u64 v[94:95], v[94:95], 0, v[76:77]
	v_lshlrev_b32_e32 v164, 1, v173
	v_mov_b32_e32 v165, v1
	v_lshl_add_u64 v[94:95], v[94:95], 0, v[164:165]
	v_lshl_add_u64 v[102:103], v[88:89], 0, s[44:45]
	v_add_co_u32_e32 v96, vcc, s74, v94
	v_mad_u64_u32 v[104:105], s[40:41], v102, s75, v[86:87]
	s_nop 0
	v_addc_co_u32_e32 v97, vcc, 0, v95, vcc
	v_mad_i32_i24 v105, v103, s75, v105
	v_add_co_u32_e32 v98, vcc, s7, v94
	v_lshl_add_u64 v[102:103], v[104:105], 0, v[76:77]
	s_nop 0
	v_addc_co_u32_e32 v99, vcc, 0, v95, vcc
	v_lshl_add_u64 v[102:103], v[102:103], 0, v[164:165]
	global_load_dwordx4 v[94:97], v[96:97], off
	s_nop 0
	global_load_dwordx4 v[98:101], v[98:99], off offset:1024
	v_add_co_u32_e32 v104, vcc, s74, v102
	v_lshl_add_u64 v[110:111], v[88:89], 0, s[46:47]
	s_nop 0
	v_addc_co_u32_e32 v105, vcc, 0, v103, vcc
	v_add_co_u32_e32 v106, vcc, s7, v102
	v_mad_u64_u32 v[112:113], s[40:41], v110, s75, v[86:87]
	s_nop 0
	v_addc_co_u32_e32 v107, vcc, 0, v103, vcc
	global_load_dwordx4 v[102:105], v[104:105], off
	s_nop 0
	global_load_dwordx4 v[106:109], v[106:107], off offset:1024
	v_mad_i32_i24 v113, v111, s75, v113
	v_lshl_add_u64 v[110:111], v[112:113], 0, v[76:77]
	v_lshl_add_u64 v[110:111], v[110:111], 0, v[164:165]
	v_lshl_add_u64 v[118:119], v[88:89], 0, s[48:49]
	v_add_co_u32_e32 v112, vcc, s74, v110
	v_mad_u64_u32 v[120:121], s[40:41], v118, s75, v[86:87]
	s_nop 0
	v_addc_co_u32_e32 v113, vcc, 0, v111, vcc
	v_mad_i32_i24 v121, v119, s75, v121
	v_add_co_u32_e32 v114, vcc, s7, v110
	v_lshl_add_u64 v[118:119], v[120:121], 0, v[76:77]
	s_nop 0
	v_addc_co_u32_e32 v115, vcc, 0, v111, vcc
	v_lshl_add_u64 v[118:119], v[118:119], 0, v[164:165]
	v_add_co_u32_e32 v120, vcc, s74, v118
	global_load_dwordx4 v[110:113], v[112:113], off
	s_nop 0
	global_load_dwordx4 v[114:117], v[114:115], off offset:1024
	v_addc_co_u32_e32 v121, vcc, 0, v119, vcc
	v_add_co_u32_e32 v122, vcc, s7, v118
	s_add_i32 s44, s24, 0x100
	s_nop 0
	v_addc_co_u32_e32 v123, vcc, 0, v119, vcc
	global_load_dwordx4 v[118:121], v[120:121], off
	s_nop 0
	global_load_dwordx4 v[122:125], v[122:123], off offset:1024
	s_mov_b32 s45, s25
	v_lshl_add_u64 v[126:127], v[88:89], 0, s[44:45]
	v_mad_u64_u32 v[128:129], s[40:41], v126, s75, v[86:87]
	v_mad_i32_i24 v129, v127, s75, v129
	v_lshl_add_u64 v[126:127], v[128:129], 0, v[76:77]
	s_add_i32 s42, s24, 0x140
	s_mov_b32 s43, s25
	v_lshl_add_u64 v[126:127], v[126:127], 0, v[164:165]
	v_lshl_add_u64 v[134:135], v[88:89], 0, s[42:43]
	v_add_co_u32_e32 v128, vcc, s74, v126
	v_mad_u64_u32 v[136:137], s[40:41], v134, s75, v[86:87]
	s_nop 0
	v_addc_co_u32_e32 v129, vcc, 0, v127, vcc
	v_mad_i32_i24 v137, v135, s75, v137
	v_add_co_u32_e32 v130, vcc, s7, v126
	v_lshl_add_u64 v[134:135], v[136:137], 0, v[76:77]
	s_nop 0
	v_addc_co_u32_e32 v131, vcc, 0, v127, vcc
	v_lshl_add_u64 v[134:135], v[134:135], 0, v[164:165]
	v_add_co_u32_e32 v136, vcc, s74, v134
	global_load_dwordx4 v[126:129], v[128:129], off
	s_nop 0
	global_load_dwordx4 v[130:133], v[130:131], off offset:1024
	v_addc_co_u32_e32 v137, vcc, 0, v135, vcc
	v_add_co_u32_e32 v138, vcc, s7, v134
	s_add_i32 s40, s24, 0x180
	s_nop 0
	v_addc_co_u32_e32 v139, vcc, 0, v135, vcc
	global_load_dwordx4 v[134:137], v[136:137], off
	s_nop 0
	global_load_dwordx4 v[138:141], v[138:139], off offset:1024
	s_mov_b32 s41, s25
	v_lshl_add_u64 v[142:143], v[88:89], 0, s[40:41]
	v_mad_u64_u32 v[144:145], s[46:47], v142, s75, v[86:87]
	v_mad_i32_i24 v145, v143, s75, v145
	v_lshl_add_u64 v[142:143], v[144:145], 0, v[76:77]
	s_addk_i32 s24, 0x1c0
	v_lshl_add_u64 v[142:143], v[142:143], 0, v[164:165]
	v_lshl_add_u64 v[88:89], v[88:89], 0, s[24:25]
	v_add_co_u32_e32 v144, vcc, s74, v142
	v_mad_u64_u32 v[166:167], s[46:47], v88, s75, v[86:87]
	s_nop 0
	v_addc_co_u32_e32 v145, vcc, 0, v143, vcc
	v_mad_i32_i24 v167, v89, s75, v167
	v_add_co_u32_e32 v160, vcc, s7, v142
	v_lshl_add_u64 v[88:89], v[166:167], 0, v[76:77]
	s_nop 0
	v_addc_co_u32_e32 v161, vcc, 0, v143, vcc
	v_lshl_add_u64 v[88:89], v[88:89], 0, v[164:165]
	v_add_co_u32_e32 v164, vcc, s74, v88
	global_load_dwordx4 v[142:145], v[144:145], off
	s_nop 0
	global_load_dwordx4 v[160:163], v[160:161], off offset:1024
	v_addc_co_u32_e32 v165, vcc, 0, v89, vcc
	v_add_co_u32_e32 v88, vcc, s7, v88
	s_mov_b32 s13, 0x10400
	s_nop 0
	v_addc_co_u32_e32 v89, vcc, 0, v89, vcc
	global_load_dwordx4 v[164:167], v[164:165], off
	s_nop 0
	global_load_dwordx4 v[168:171], v[88:89], off offset:1024
	v_add_u32_e32 v208, s44, v82
	v_mad_u64_u32 v[206:207], s[98:99], v208, s75, v[86:87]
	v_lshl_add_u64 v[206:207], v[206:207], 0, v[76:77]
	v_lshl_add_u64 v[206:207], v[206:207], 0, v[252:253]
	global_load_dwordx4 v[210:213], v[206:207], off offset:3072
	global_load_dwordx4 v[214:217], v[206:207], off offset:3136
	v_add_u32_e32 v208, s44, v84
	v_mad_u64_u32 v[206:207], s[98:99], v208, s75, v[86:87]
	v_lshl_add_u64 v[206:207], v[206:207], 0, v[76:77]
	v_lshl_add_u64 v[206:207], v[206:207], 0, v[252:253]
	global_load_dwordx4 v[218:221], v[206:207], off offset:3072
	global_load_dwordx4 v[222:225], v[206:207], off offset:3136
	v_add_u32_e32 v208, s42, v82
	v_mad_u64_u32 v[206:207], s[98:99], v208, s75, v[86:87]
	v_lshl_add_u64 v[206:207], v[206:207], 0, v[76:77]
	v_lshl_add_u64 v[206:207], v[206:207], 0, v[252:253]
	global_load_dwordx4 v[226:229], v[206:207], off offset:3072
	global_load_dwordx4 v[230:233], v[206:207], off offset:3136
	v_add_u32_e32 v208, s42, v84
	v_mad_u64_u32 v[206:207], s[98:99], v208, s75, v[86:87]
	v_lshl_add_u64 v[206:207], v[206:207], 0, v[76:77]
	v_lshl_add_u64 v[206:207], v[206:207], 0, v[252:253]
	global_load_dwordx4 v[234:237], v[206:207], off offset:3072
	s_waitcnt vmcnt(25)
; __device__ __forceinline__ void na2_task(const Params& p_, int l, int task, unsigned char* lds) {
;     ...
;     { const int pair = lane & 31, chunk = (lane >> 5) + 2 * (w & 3);
;       unsigned* VTd = (unsigned*)(VT + (size_t)hh * 64 * 520);
;       u32x4 xs[8], ys[8];
; #pragma unroll
;       for (int a = 0; a < 8; ++a) { const size_t tok = (size_t)b * SEQ + (row_start + a) * 64 + 2 * pair;
;           const bf16* src = Z + tok * DIN + 4 * DG + h * 64 + chunk * 8; xs[a] = *(const u32x4*)src; ys[a] = *(const u32x4*)(src + DIN); }
;       asm volatile("" ::: "memory");
; #pragma unroll
;       for (int a = 0; a < 8; ++a) { const unsigned xu[4] = {xs[a].x, xs[a].y, xs[a].z, xs[a].w}, yu[4] = {ys[a].x, ys[a].y, ys[a].z, ys[a].w};
; #pragma unroll
;           for (int i = 0; i < 4; ++i) { VTd[(chunk * 8 + 2 * i) * 260 + a * 32 + pair] = (xu[i] & 0xffffu) | (yu[i] << 16);
;               VTd[(chunk * 8 + 2 * i + 1) * 260 + a * 32 + pair] = (xu[i] >> 16) | (yu[i] & 0xffff0000u); } } }
	ds_bpermute_b32 v70, v251, v70
	ds_bpermute_b32 v71, v251, v71
	ds_bpermute_b32 v72, v251, v72
	ds_bpermute_b32 v73, v251, v73
	ds_bpermute_b32 v66, v251, v66
	ds_bpermute_b32 v67, v251, v67
	ds_bpermute_b32 v68, v251, v68
	ds_bpermute_b32 v69, v251, v69
	ds_bpermute_b32 v62, v251, v62
	ds_bpermute_b32 v63, v251, v63
	ds_bpermute_b32 v64, v251, v64
	ds_bpermute_b32 v65, v251, v65
	ds_bpermute_b32 v58, v251, v58
	ds_bpermute_b32 v59, v251, v59
	ds_bpermute_b32 v60, v251, v60
	ds_bpermute_b32 v61, v251, v61
	ds_bpermute_b32 v18, v251, v18
	ds_bpermute_b32 v19, v251, v19
	ds_bpermute_b32 v20, v251, v20
	ds_bpermute_b32 v21, v251, v21
	ds_bpermute_b32 v10, v251, v10
	ds_bpermute_b32 v11, v251, v11
	ds_bpermute_b32 v12, v251, v12
	ds_bpermute_b32 v13, v251, v13
	ds_bpermute_b32 v38, v251, v38
	ds_bpermute_b32 v39, v251, v39
	ds_bpermute_b32 v40, v251, v40
	ds_bpermute_b32 v41, v251, v41
	ds_bpermute_b32 v22, v251, v22
	ds_bpermute_b32 v23, v251, v23
	ds_bpermute_b32 v24, v251, v24
	ds_bpermute_b32 v25, v251, v25
	ds_bpermute_b32 v54, v251, v54
	ds_bpermute_b32 v55, v251, v55
	ds_bpermute_b32 v56, v251, v56
	ds_bpermute_b32 v57, v251, v57
	ds_bpermute_b32 v42, v251, v42
	ds_bpermute_b32 v43, v251, v43
	ds_bpermute_b32 v44, v251, v44
	ds_bpermute_b32 v45, v251, v45
	ds_bpermute_b32 v46, v251, v46
	ds_bpermute_b32 v47, v251, v47
	ds_bpermute_b32 v48, v251, v48
	ds_bpermute_b32 v49, v251, v49
	ds_bpermute_b32 v30, v251, v30
	ds_bpermute_b32 v31, v251, v31
	ds_bpermute_b32 v32, v251, v32
	ds_bpermute_b32 v33, v251, v33
	ds_bpermute_b32 v26, v251, v26
	ds_bpermute_b32 v27, v251, v27
	ds_bpermute_b32 v28, v251, v28
	ds_bpermute_b32 v29, v251, v29
	ds_bpermute_b32 v14, v251, v14
	ds_bpermute_b32 v15, v251, v15
	ds_bpermute_b32 v16, v251, v16
	ds_bpermute_b32 v17, v251, v17
	ds_bpermute_b32 v50, v251, v50
	ds_bpermute_b32 v51, v251, v51
	ds_bpermute_b32 v52, v251, v52
	ds_bpermute_b32 v53, v251, v53
	ds_bpermute_b32 v34, v251, v34
	ds_bpermute_b32 v35, v251, v35
	ds_bpermute_b32 v36, v251, v36
	ds_bpermute_b32 v37, v251, v37
	s_waitcnt vmcnt(7)
	v_and_b32_e32 v248, 1, v147
	v_cmp_eq_u32_e32 vcc, 1, v248
	s_nop 1
	v_mov_b32_e32 v249, v94
	v_cndmask_b32_e32 v94, v94, v95, vcc
	v_cndmask_b32_e32 v95, v95, v96, vcc
	v_cndmask_b32_e32 v96, v96, v97, vcc
	v_cndmask_b32_e32 v97, v97, v249, vcc
	v_mov_b32_e32 v249, v98
	v_cndmask_b32_e32 v98, v98, v99, vcc
	v_cndmask_b32_e32 v99, v99, v100, vcc
	v_cndmask_b32_e32 v100, v100, v101, vcc
	v_cndmask_b32_e32 v101, v101, v249, vcc
	v_mov_b32_e32 v249, v102
	v_cndmask_b32_e32 v102, v102, v103, vcc
	v_cndmask_b32_e32 v103, v103, v104, vcc
	v_cndmask_b32_e32 v104, v104, v105, vcc
	v_cndmask_b32_e32 v105, v105, v249, vcc
	v_mov_b32_e32 v249, v106
	v_cndmask_b32_e32 v106, v106, v107, vcc
	v_cndmask_b32_e32 v107, v107, v108, vcc
	v_cndmask_b32_e32 v108, v108, v109, vcc
	v_cndmask_b32_e32 v109, v109, v249, vcc
	v_mov_b32_e32 v249, v110
	v_cndmask_b32_e32 v110, v110, v111, vcc
	v_cndmask_b32_e32 v111, v111, v112, vcc
	v_cndmask_b32_e32 v112, v112, v113, vcc
	v_cndmask_b32_e32 v113, v113, v249, vcc
	v_mov_b32_e32 v249, v114
	v_cndmask_b32_e32 v114, v114, v115, vcc
	v_cndmask_b32_e32 v115, v115, v116, vcc
	v_cndmask_b32_e32 v116, v116, v117, vcc
	v_cndmask_b32_e32 v117, v117, v249, vcc
	v_mov_b32_e32 v249, v118
	v_cndmask_b32_e32 v118, v118, v119, vcc
	v_cndmask_b32_e32 v119, v119, v120, vcc
	v_cndmask_b32_e32 v120, v120, v121, vcc
	v_cndmask_b32_e32 v121, v121, v249, vcc
	v_mov_b32_e32 v249, v122
	v_cndmask_b32_e32 v122, v122, v123, vcc
	v_cndmask_b32_e32 v123, v123, v124, vcc
	v_cndmask_b32_e32 v124, v124, v125, vcc
	v_cndmask_b32_e32 v125, v125, v249, vcc
	v_mov_b32_e32 v249, v126
	v_cndmask_b32_e32 v126, v126, v127, vcc
	v_cndmask_b32_e32 v127, v127, v128, vcc
	v_cndmask_b32_e32 v128, v128, v129, vcc
	v_cndmask_b32_e32 v129, v129, v249, vcc
	v_mov_b32_e32 v249, v130
	v_cndmask_b32_e32 v130, v130, v131, vcc
	v_cndmask_b32_e32 v131, v131, v132, vcc
	v_cndmask_b32_e32 v132, v132, v133, vcc
	v_cndmask_b32_e32 v133, v133, v249, vcc
	v_mov_b32_e32 v249, v134
	v_cndmask_b32_e32 v134, v134, v135, vcc
	v_cndmask_b32_e32 v135, v135, v136, vcc
	v_cndmask_b32_e32 v136, v136, v137, vcc
	v_cndmask_b32_e32 v137, v137, v249, vcc
	v_mov_b32_e32 v249, v138
	v_cndmask_b32_e32 v138, v138, v139, vcc
	v_cndmask_b32_e32 v139, v139, v140, vcc
	v_cndmask_b32_e32 v140, v140, v141, vcc
	v_cndmask_b32_e32 v141, v141, v249, vcc
	v_mov_b32_e32 v249, v142
	v_cndmask_b32_e32 v142, v142, v143, vcc
	v_cndmask_b32_e32 v143, v143, v144, vcc
	v_cndmask_b32_e32 v144, v144, v145, vcc
	v_cndmask_b32_e32 v145, v145, v249, vcc
	v_mov_b32_e32 v249, v160
	v_cndmask_b32_e32 v160, v160, v161, vcc
	v_cndmask_b32_e32 v161, v161, v162, vcc
	v_cndmask_b32_e32 v162, v162, v163, vcc
	v_cndmask_b32_e32 v163, v163, v249, vcc
	v_mov_b32_e32 v249, v164
	v_cndmask_b32_e32 v164, v164, v165, vcc
	v_cndmask_b32_e32 v165, v165, v166, vcc
	v_cndmask_b32_e32 v166, v166, v167, vcc
	v_cndmask_b32_e32 v167, v167, v249, vcc
	v_mov_b32_e32 v249, v168
	v_cndmask_b32_e32 v168, v168, v169, vcc
	v_cndmask_b32_e32 v169, v169, v170, vcc
	v_cndmask_b32_e32 v170, v170, v171, vcc
	v_cndmask_b32_e32 v171, v171, v249, vcc
	v_and_b32_e32 v248, 2, v147
	v_cmp_eq_u32_e32 vcc, 2, v248
	s_nop 1
	v_mov_b32_e32 v249, v94
	v_cndmask_b32_e32 v94, v94, v96, vcc
	v_cndmask_b32_e32 v96, v96, v249, vcc
	v_mov_b32_e32 v249, v95
	v_cndmask_b32_e32 v95, v95, v97, vcc
	v_cndmask_b32_e32 v97, v97, v249, vcc
	v_mov_b32_e32 v249, v98
	v_cndmask_b32_e32 v98, v98, v100, vcc
	v_cndmask_b32_e32 v100, v100, v249, vcc
	v_mov_b32_e32 v249, v99
	v_cndmask_b32_e32 v99, v99, v101, vcc
	v_cndmask_b32_e32 v101, v101, v249, vcc
; __device__ __forceinline__ void na2_task(const Params& p_, int l, int task, unsigned char* lds) {
;     ...
; #pragma unroll
;       for (int a = 0; a < 8; ++a) { const unsigned xu[4] = {xs[a].x, xs[a].y, xs[a].z, xs[a].w}, yu[4] = {ys[a].x, ys[a].y, ys[a].z, ys[a].w};
; #pragma unroll
;           for (int i = 0; i < 4; ++i) { VTd[(chunk * 8 + 2 * i) * 260 + a * 32 + pair] = (xu[i] & 0xffffu) | (yu[i] << 16);
;               VTd[(chunk * 8 + 2 * i + 1) * 260 + a * 32 + pair] = (xu[i] >> 16) | (yu[i] & 0xffff0000u); } } }
	v_mov_b32_e32 v249, v102
	v_cndmask_b32_e32 v102, v102, v104, vcc
	v_cndmask_b32_e32 v104, v104, v249, vcc
	v_mov_b32_e32 v249, v103
	v_cndmask_b32_e32 v103, v103, v105, vcc
	v_cndmask_b32_e32 v105, v105, v249, vcc
	v_mov_b32_e32 v249, v106
	v_cndmask_b32_e32 v106, v106, v108, vcc
	v_cndmask_b32_e32 v108, v108, v249, vcc
	v_mov_b32_e32 v249, v107
	v_cndmask_b32_e32 v107, v107, v109, vcc
	v_cndmask_b32_e32 v109, v109, v249, vcc
	v_mov_b32_e32 v249, v110
	v_cndmask_b32_e32 v110, v110, v112, vcc
	v_cndmask_b32_e32 v112, v112, v249, vcc
	v_mov_b32_e32 v249, v111
	v_cndmask_b32_e32 v111, v111, v113, vcc
	v_cndmask_b32_e32 v113, v113, v249, vcc
	v_mov_b32_e32 v249, v114
	v_cndmask_b32_e32 v114, v114, v116, vcc
	v_cndmask_b32_e32 v116, v116, v249, vcc
	v_mov_b32_e32 v249, v115
	v_cndmask_b32_e32 v115, v115, v117, vcc
	v_cndmask_b32_e32 v117, v117, v249, vcc
	v_mov_b32_e32 v249, v118
	v_cndmask_b32_e32 v118, v118, v120, vcc
	v_cndmask_b32_e32 v120, v120, v249, vcc
	v_mov_b32_e32 v249, v119
	v_cndmask_b32_e32 v119, v119, v121, vcc
	v_cndmask_b32_e32 v121, v121, v249, vcc
	v_mov_b32_e32 v249, v122
	v_cndmask_b32_e32 v122, v122, v124, vcc
	v_cndmask_b32_e32 v124, v124, v249, vcc
	v_mov_b32_e32 v249, v123
	v_cndmask_b32_e32 v123, v123, v125, vcc
	v_cndmask_b32_e32 v125, v125, v249, vcc
	v_mov_b32_e32 v249, v126
	v_cndmask_b32_e32 v126, v126, v128, vcc
	v_cndmask_b32_e32 v128, v128, v249, vcc
	v_mov_b32_e32 v249, v127
	v_cndmask_b32_e32 v127, v127, v129, vcc
	v_cndmask_b32_e32 v129, v129, v249, vcc
	v_mov_b32_e32 v249, v130
	v_cndmask_b32_e32 v130, v130, v132, vcc
	v_cndmask_b32_e32 v132, v132, v249, vcc
	v_mov_b32_e32 v249, v131
	v_cndmask_b32_e32 v131, v131, v133, vcc
	v_cndmask_b32_e32 v133, v133, v249, vcc
	v_mov_b32_e32 v249, v134
	v_cndmask_b32_e32 v134, v134, v136, vcc
	v_cndmask_b32_e32 v136, v136, v249, vcc
	v_mov_b32_e32 v249, v135
	v_cndmask_b32_e32 v135, v135, v137, vcc
	v_cndmask_b32_e32 v137, v137, v249, vcc
	v_mov_b32_e32 v249, v138
	v_cndmask_b32_e32 v138, v138, v140, vcc
	v_cndmask_b32_e32 v140, v140, v249, vcc
	v_mov_b32_e32 v249, v139
	v_cndmask_b32_e32 v139, v139, v141, vcc
	v_cndmask_b32_e32 v141, v141, v249, vcc
	v_mov_b32_e32 v249, v142
	v_cndmask_b32_e32 v142, v142, v144, vcc
	v_cndmask_b32_e32 v144, v144, v249, vcc
	v_mov_b32_e32 v249, v143
	v_cndmask_b32_e32 v143, v143, v145, vcc
	v_cndmask_b32_e32 v145, v145, v249, vcc
	v_mov_b32_e32 v249, v160
	v_cndmask_b32_e32 v160, v160, v162, vcc
	v_cndmask_b32_e32 v162, v162, v249, vcc
	v_mov_b32_e32 v249, v161
	v_cndmask_b32_e32 v161, v161, v163, vcc
	v_cndmask_b32_e32 v163, v163, v249, vcc
	v_mov_b32_e32 v249, v164
	v_cndmask_b32_e32 v164, v164, v166, vcc
	v_cndmask_b32_e32 v166, v166, v249, vcc
	v_mov_b32_e32 v249, v165
	v_cndmask_b32_e32 v165, v165, v167, vcc
	v_cndmask_b32_e32 v167, v167, v249, vcc
	v_mov_b32_e32 v249, v168
	v_cndmask_b32_e32 v168, v168, v170, vcc
	v_cndmask_b32_e32 v170, v170, v249, vcc
	v_mov_b32_e32 v249, v169
	v_cndmask_b32_e32 v169, v169, v171, vcc
	v_cndmask_b32_e32 v171, v171, v249, vcc
	s_waitcnt lgkmcnt(0)
	v_and_b32_e32 v89, 0xffff, v94
	v_lshrrev_b32_e32 v94, 16, v94
	v_lshl_or_b32 v89, v98, 16, v89
	v_and_or_b32 v94, v98, s15, v94
	v_and_b32_e32 v98, 0xffff, v95
	v_lshrrev_b32_e32 v95, 16, v95
	v_lshl_or_b32 v98, v99, 16, v98
	v_and_or_b32 v95, v99, s15, v95
	v_and_b32_e32 v99, 0xffff, v96
	v_lshrrev_b32_e32 v96, 16, v96
	v_lshlrev_b32_e32 v88, 2, v172
	v_mul_u32_u24_e32 v172, 0x104, v173
	v_lshl_or_b32 v99, v100, 16, v99
	v_and_or_b32 v96, v100, s15, v96
	v_and_b32_e32 v100, 0xffff, v97
	v_lshrrev_b32_e32 v97, 16, v97
	v_mad_i32_i24 v81, v93, s13, 0
	v_lshlrev_b32_e32 v172, 2, v172
	v_lshl_or_b32 v100, v101, 16, v100
	v_and_or_b32 v97, v101, s15, v97
	v_and_b32_e32 v101, 0xffff, v102
	v_add3_u32 v173, v81, v88, v172
	v_and_b32_e32 v248, 3, v147
	v_add_u32_e32 v249, 0, v248
	v_and_b32_e32 v249, 3, v249
	v_mul_u32_u24_e32 v249, 0x820, v249
	v_add_u32_e32 v238, v173, v249
	v_add_u32_e32 v239, 0x410, v238
	v_add_u32_e32 v249, 1, v248
	v_and_b32_e32 v249, 3, v249
	v_mul_u32_u24_e32 v249, 0x820, v249
	v_add_u32_e32 v240, v173, v249
	v_add_u32_e32 v241, 0x410, v240
	v_add_u32_e32 v249, 2, v248
	v_and_b32_e32 v249, 3, v249
	v_mul_u32_u24_e32 v249, 0x820, v249
	v_add_u32_e32 v242, v173, v249
	v_add_u32_e32 v243, 0x410, v242
	v_add_u32_e32 v249, 3, v248
	v_and_b32_e32 v249, 3, v249
	v_mul_u32_u24_e32 v249, 0x820, v249
	v_add_u32_e32 v244, v173, v249
	v_add_u32_e32 v245, 0x410, v244
	v_lshl_or_b32 v101, v106, 16, v101
	v_add3_u32 v88, v81, v172, v88
	ds_write2_b32 v238, v89, v101 offset1:32
	v_lshrrev_b32_e32 v89, 16, v102
	v_and_or_b32 v89, v106, s15, v89
	v_add_u32_e32 v101, 0x400, v88
	ds_write2_b32 v239, v94, v89 offset1:32
	v_and_b32_e32 v89, 0xffff, v103
	v_lshl_or_b32 v89, v107, 16, v89
	v_add_u32_e32 v94, 0x800, v173
	ds_write2_b32 v240, v98, v89 offset1:32
	v_lshrrev_b32_e32 v89, 16, v103
	v_and_or_b32 v89, v107, s15, v89
	v_add_u32_e32 v98, 0xc00, v88
	ds_write2_b32 v241, v95, v89 offset1:32
	v_and_b32_e32 v89, 0xffff, v104
	v_lshl_or_b32 v89, v108, 16, v89
	v_add_u32_e32 v95, 0x1000, v173
	ds_write2_b32 v242, v99, v89 offset1:32
	v_lshrrev_b32_e32 v89, 16, v104
	v_and_or_b32 v89, v108, s15, v89
	v_add_u32_e32 v99, 0x1400, v88
	ds_write2_b32 v243, v96, v89 offset1:32
	v_and_b32_e32 v89, 0xffff, v105
	v_lshl_or_b32 v89, v109, 16, v89
	v_add_u32_e32 v96, 0x1800, v173
	ds_write2_b32 v244, v100, v89 offset1:32
	v_lshrrev_b32_e32 v89, 16, v105
	v_and_or_b32 v89, v109, s15, v89
	v_add_u32_e32 v88, 0x1c00, v88
	ds_write2_b32 v245, v97, v89 offset1:32
	v_and_b32_e32 v89, 0xffff, v110
	v_and_b32_e32 v107, 0xffff, v118
	v_lshl_or_b32 v89, v114, 16, v89
; #define MFMA16(a, b, c) __builtin_amdgcn_mfma_f32_16x16x32_bf16(a, b, c, 0, 0, 0)
; __device__ __forceinline__ void na2_task(const Params& p_, int l, int task, unsigned char* lds) {
;     ...
; #pragma unroll
;       for (int a = 0; a < 8; ++a) { const unsigned xu[4] = {xs[a].x, xs[a].y, xs[a].z, xs[a].w}, yu[4] = {ys[a].x, ys[a].y, ys[a].z, ys[a].w};
; #pragma unroll
;           for (int i = 0; i < 4; ++i) { VTd[(chunk * 8 + 2 * i) * 260 + a * 32 + pair] = (xu[i] & 0xffffu) | (yu[i] << 16);
;               VTd[(chunk * 8 + 2 * i + 1) * 260 + a * 32 + pair] = (xu[i] >> 16) | (yu[i] & 0xffff0000u); } } }
;     ...
; #pragma unroll
;         for (int i = 0; i < 8; ++i) { const int a = 4 * hf + i / 2, ci = i % 2, kt = a * 2 + ci;
;             f32x4 acc = {0.f, 0.f, 0.f, 0.f};
; #pragma unroll
;             for (int ks = 0; ks < 2; ++ks) acc = MFMA16(kfr[i][ks], qf[ks], acc);
	v_lshl_or_b32 v107, v122, 16, v107
	v_lshrrev_b32_e32 v97, 16, v110
	ds_write2_b32 v238, v89, v107 offset0:64 offset1:96
	v_lshrrev_b32_e32 v89, 16, v118
	v_and_or_b32 v97, v114, s15, v97
	v_and_or_b32 v89, v122, s15, v89
	v_and_b32_e32 v100, 0xffff, v111
	ds_write2_b32 v239, v97, v89 offset0:64 offset1:96
	v_and_b32_e32 v89, 0xffff, v119
	v_lshl_or_b32 v100, v115, 16, v100
	v_lshl_or_b32 v89, v123, 16, v89
	v_lshrrev_b32_e32 v102, 16, v111
	ds_write2_b32 v240, v100, v89 offset0:64 offset1:96
	v_lshrrev_b32_e32 v89, 16, v119
	v_and_or_b32 v102, v115, s15, v102
	v_and_or_b32 v89, v123, s15, v89
	v_and_b32_e32 v103, 0xffff, v112
	ds_write2_b32 v241, v102, v89 offset0:64 offset1:96
	v_and_b32_e32 v89, 0xffff, v120
	v_lshl_or_b32 v103, v116, 16, v103
	v_lshl_or_b32 v89, v124, 16, v89
	v_lshrrev_b32_e32 v104, 16, v112
	ds_write2_b32 v242, v103, v89 offset0:64 offset1:96
	v_lshrrev_b32_e32 v89, 16, v120
	v_and_or_b32 v104, v116, s15, v104
	v_and_or_b32 v89, v124, s15, v89
	v_and_b32_e32 v105, 0xffff, v113
	ds_write2_b32 v243, v104, v89 offset0:64 offset1:96
	v_and_b32_e32 v89, 0xffff, v121
	v_lshl_or_b32 v105, v117, 16, v105
	v_lshl_or_b32 v89, v125, 16, v89
	v_lshrrev_b32_e32 v106, 16, v113
	ds_write2_b32 v244, v105, v89 offset0:64 offset1:96
	v_lshrrev_b32_e32 v89, 16, v121
	v_and_or_b32 v106, v117, s15, v106
	v_and_or_b32 v89, v125, s15, v89
	ds_write2_b32 v245, v106, v89 offset0:64 offset1:96
	v_and_b32_e32 v89, 0xffff, v126
	v_and_b32_e32 v107, 0xffff, v134
	v_lshl_or_b32 v89, v130, 16, v89
	v_lshl_or_b32 v107, v138, 16, v107
	v_lshrrev_b32_e32 v97, 16, v126
	ds_write2_b32 v238, v89, v107 offset0:128 offset1:160
	v_lshrrev_b32_e32 v89, 16, v134
	v_and_or_b32 v97, v130, s15, v97
	v_and_or_b32 v89, v138, s15, v89
	v_and_b32_e32 v100, 0xffff, v127
	ds_write2_b32 v239, v97, v89 offset0:128 offset1:160
	v_and_b32_e32 v89, 0xffff, v135
	v_lshl_or_b32 v100, v131, 16, v100
	v_lshl_or_b32 v89, v139, 16, v89
	v_lshrrev_b32_e32 v102, 16, v127
	ds_write2_b32 v240, v100, v89 offset0:128 offset1:160
	v_lshrrev_b32_e32 v89, 16, v135
	v_and_or_b32 v102, v131, s15, v102
	v_and_or_b32 v89, v139, s15, v89
	v_and_b32_e32 v103, 0xffff, v128
	ds_write2_b32 v241, v102, v89 offset0:128 offset1:160
	v_and_b32_e32 v89, 0xffff, v136
	v_lshl_or_b32 v103, v132, 16, v103
	v_lshl_or_b32 v89, v140, 16, v89
	v_lshrrev_b32_e32 v104, 16, v128
	ds_write2_b32 v242, v103, v89 offset0:128 offset1:160
	v_lshrrev_b32_e32 v89, 16, v136
	v_and_or_b32 v104, v132, s15, v104
	v_and_or_b32 v89, v140, s15, v89
	v_and_b32_e32 v105, 0xffff, v129
	ds_write2_b32 v243, v104, v89 offset0:128 offset1:160
	v_and_b32_e32 v89, 0xffff, v137
	v_lshl_or_b32 v105, v133, 16, v105
	v_lshl_or_b32 v89, v141, 16, v89
	v_lshrrev_b32_e32 v106, 16, v129
	ds_write2_b32 v244, v105, v89 offset0:128 offset1:160
	v_lshrrev_b32_e32 v89, 16, v137
	v_and_or_b32 v106, v133, s15, v106
	v_and_or_b32 v89, v141, s15, v89
	ds_write2_b32 v245, v106, v89 offset0:128 offset1:160
	v_and_b32_e32 v89, 0xffff, v142
	v_and_b32_e32 v107, 0xffff, v164
	v_lshl_or_b32 v89, v160, 16, v89
	v_lshl_or_b32 v107, v168, 16, v107
	v_lshrrev_b32_e32 v97, 16, v142
	ds_write2_b32 v238, v89, v107 offset0:192 offset1:224
	v_lshrrev_b32_e32 v89, 16, v164
	v_and_or_b32 v97, v160, s15, v97
	v_and_or_b32 v89, v168, s15, v89
	v_and_b32_e32 v100, 0xffff, v143
	ds_write2_b32 v239, v97, v89 offset0:192 offset1:224
	v_and_b32_e32 v89, 0xffff, v165
	v_lshl_or_b32 v100, v161, 16, v100
	v_lshl_or_b32 v89, v169, 16, v89
	v_lshrrev_b32_e32 v102, 16, v143
	ds_write2_b32 v240, v100, v89 offset0:192 offset1:224
	v_lshrrev_b32_e32 v89, 16, v165
	v_and_or_b32 v102, v161, s15, v102
	v_and_or_b32 v89, v169, s15, v89
	v_and_b32_e32 v103, 0xffff, v144
	ds_write2_b32 v241, v102, v89 offset0:192 offset1:224
	v_and_b32_e32 v89, 0xffff, v166
	v_lshl_or_b32 v103, v162, 16, v103
	v_lshl_or_b32 v89, v170, 16, v89
	v_lshrrev_b32_e32 v104, 16, v144
	ds_write2_b32 v242, v103, v89 offset0:192 offset1:224
	v_lshrrev_b32_e32 v89, 16, v166
	v_and_or_b32 v104, v162, s15, v104
	v_and_or_b32 v89, v170, s15, v89
	v_and_b32_e32 v105, 0xffff, v145
	ds_write2_b32 v243, v104, v89 offset0:192 offset1:224
	v_and_b32_e32 v89, 0xffff, v167
	v_lshl_or_b32 v105, v163, 16, v105
	v_lshl_or_b32 v89, v171, 16, v89
	v_mfma_f32_16x16x32_bf16 v[62:65], v[62:65], v[6:9], 0
	v_lshrrev_b32_e32 v106, 16, v145
	ds_write2_b32 v244, v105, v89 offset0:192 offset1:224
	v_lshrrev_b32_e32 v89, 16, v167
	s_sub_i32 s9, s12, s9
	v_mfma_f32_16x16x32_bf16 v[70:73], v[70:73], v[6:9], 0
	v_lshl_add_u32 v168, v92, 2, v80
	v_and_or_b32 v106, v163, s15, v106
	v_and_or_b32 v89, v171, s15, v89
	s_mulk_i32 s9, 0x7c
	v_add_u32_e32 v169, 16, v168
	ds_write2_b32 v245, v106, v89 offset0:192 offset1:224
	s_add_i32 s9, s9, 0
	v_sub_u32_e32 v88, v169, v91
	s_add_i32 s9, s9, 0x20800
	v_mfma_f32_16x16x32_bf16 v[58:61], v[58:61], v[2:5], v[62:65]
	v_add_u32_e32 v173, 17, v168
	v_add_u32_e32 v174, 18, v168
	v_or_b32_e32 v170, 1, v168
	v_max_i32_e32 v62, -15, v88
	v_mfma_f32_16x16x32_bf16 v[94:97], v[66:69], v[2:5], v[70:73]
	v_mov_b32_e32 v66, s9
	s_movk_i32 s9, 0x744
	v_add_u32_e32 v62, 15, v62
	v_mad_i32_i24 v98, v93, s9, v66
	v_min_u32_e32 v62, 30, v62
	v_lshl_add_u32 v103, v62, 2, v98
	v_sub_u32_e32 v62, v173, v91
	v_mfma_f32_16x16x32_bf16 v[18:21], v[18:21], v[6:9], 0
	v_max_i32_e32 v62, -15, v62
	v_add_u32_e32 v62, 15, v62
	v_min_u32_e32 v62, 30, v62
	v_lshl_add_u32 v104, v62, 2, v98
	v_mfma_f32_16x16x32_bf16 v[62:65], v[10:13], v[2:5], v[18:21]
	v_sub_u32_e32 v10, v174, v91
	v_or_b32_e32 v171, 2, v168
	v_or_b32_e32 v172, 3, v168
	v_max_i32_e32 v18, -15, v10
	v_mfma_f32_16x16x32_bf16 v[10:13], v[38:41], v[6:9], 0
; #define MFMA16(a, b, c) __builtin_amdgcn_mfma_f32_16x16x32_bf16(a, b, c, 0, 0, 0)
; __device__ __forceinline__ void na2_task(const Params& p_, int l, int task, unsigned char* lds) {
;     ...
;     __syncthreads();
;     const int col_start = min(max(c - 8, 0), 48);
;     const float* bi = BI + hh * 465;
;     float sc[16][4]; float mx = -1e30f;
; #pragma unroll
;     for (int hf = 0; hf < 2; ++hf) {
;         if (hf == 1) {
; #pragma unroll
;             for (int i = 0; i < 8; ++i) { const int a = 4 + i / 2, ci = i % 2;
;                 const size_t ktok = (size_t)b * SEQ + (row_start + a) * 64 + kst + 16 * ci + fr;
; #pragma unroll
;                 for (int ks = 0; ks < 2; ++ks) kfr[i][ks] = *(const bf16x8v*)(Z + ktok * DIN + 3 * DG + h * 64 + 32 * ks + 8 * fq); }
;             asm volatile("" ::: "memory");
;         }
; #pragma unroll
;         for (int i = 0; i < 8; ++i) { const int a = 4 * hf + i / 2, ci = i % 2, kt = a * 2 + ci;
;             f32x4 acc = {0.f, 0.f, 0.f, 0.f};
; #pragma unroll
;             for (int ks = 0; ks < 2; ++ks) acc = MFMA16(kfr[i][ks], qf[ks], acc);
;             const int dr = row_start + a - rq;
; #pragma unroll
;             for (int r = 0; r < 4; ++r) { const int kc = kst + 16 * ci + 4 * fq + r, rel = kc - col_start, dc = kc - c;
;                 float v = acc[r] * 0.125f + bi[(dr + 7) * 31 + min(max(dc + 15, 0), 30)];
;                 v = (rel >= 0 && rel < 16) ? v : -1e30f; sc[kt][r] = v; mx = fmaxf(mx, v); } }
	v_add_u32_e32 v175, 19, v168
	v_sub_u32_e32 v66, v168, v91
	v_sub_u32_e32 v68, v170, v91
	v_mfma_f32_16x16x32_bf16 v[38:41], v[22:25], v[2:5], v[10:13]
	v_sub_u32_e32 v70, v171, v91
	v_sub_u32_e32 v72, v172, v91
	v_sub_u32_e32 v19, v175, v91
	v_mfma_f32_16x16x32_bf16 v[10:13], v[54:57], v[6:9], 0
	v_max_i32_e32 v66, -15, v66
	v_max_i32_e32 v68, -15, v68
	v_max_i32_e32 v70, -15, v70
	v_mfma_f32_16x16x32_bf16 v[42:45], v[42:45], v[2:5], v[10:13]
	v_max_i32_e32 v72, -15, v72
	v_max_i32_e32 v19, -15, v19
	v_add_u32_e32 v66, 15, v66
	v_mfma_f32_16x16x32_bf16 v[10:13], v[46:49], v[6:9], 0
	v_add_u32_e32 v68, 15, v68
	v_add_u32_e32 v70, 15, v70
	v_add_u32_e32 v72, 15, v72
	v_mfma_f32_16x16x32_bf16 v[46:49], v[30:33], v[2:5], v[10:13]
	v_add_u32_e32 v18, 15, v18
	v_add_u32_e32 v19, 15, v19
	v_lshlrev_b32_e32 v0, 3, v92
	v_mfma_f32_16x16x32_bf16 v[10:13], v[26:29], v[6:9], 0
	v_min_u32_e32 v66, 30, v66
	v_min_u32_e32 v68, 30, v68
	v_min_u32_e32 v70, 30, v70
	v_mfma_f32_16x16x32_bf16 v[54:57], v[14:17], v[2:5], v[10:13]
	v_min_u32_e32 v72, 30, v72
	v_min_u32_e32 v18, 30, v18
	v_min_u32_e32 v19, 30, v19
	v_mfma_f32_16x16x32_bf16 v[10:13], v[50:53], v[6:9], 0
	v_lshl_add_u32 v99, v66, 2, v98
	v_lshl_add_u32 v100, v68, 2, v98
	v_lshl_add_u32 v101, v70, 2, v98
	v_mfma_f32_16x16x32_bf16 v[50:53], v[34:37], v[2:5], v[10:13]
	v_lshl_add_u32 v102, v72, 2, v98
	v_lshl_add_u32 v18, v18, 2, v98
	v_lshl_add_u32 v19, v19, 2, v98
	s_nop 0
	v_lshl_add_u64 v[10:11], v[82:83], 0, s[44:45]
	v_mad_u64_u32 v[12:13], s[12:13], v10, s75, v[86:87]
	v_mov_b32_e32 v10, v13
	v_mad_u64_u32 v[10:11], s[12:13], v11, s75, v[10:11]
	v_mov_b32_e32 v13, v10
	v_lshl_add_u64 v[10:11], v[12:13], 0, v[76:77]
	v_mov_b32_e32 v12, v252
	v_mov_b32_e32 v13, v1
	v_add_u32_e32 v176, 0x400, v99
	v_add_u32_e32 v177, 0x400, v100
	v_add_u32_e32 v197, 0x400, v101
	v_add_u32_e32 v198, 0x400, v102
	v_add_u32_e32 v199, 0x400, v103
	v_add_u32_e32 v200, 0x400, v104
	v_add_u32_e32 v201, 0x400, v18
	v_add_u32_e32 v202, 0x400, v19
	v_lshl_add_u64 v[10:11], v[10:11], 0, v[12:13]
	ds_write_b32 v204, v203
	ds_write_b32 v205, v209
	s_waitcnt lgkmcnt(0)
	s_barrier
	ds_read2_b32 v[66:67], v99 offset0:217 offset1:248
	ds_read2_b32 v[68:69], v100 offset0:217 offset1:248
	ds_read2_b32 v[70:71], v101 offset0:217 offset1:248
	ds_read2_b32 v[72:73], v102 offset0:217 offset1:248
	ds_read2_b32 v[88:89], v103 offset0:217 offset1:248
	ds_read2_b32 v[92:93], v104 offset0:217 offset1:248
	ds_read2_b32 v[134:135], v18 offset0:217 offset1:248
	ds_read2_b32 v[136:137], v19 offset0:217 offset1:248
	ds_read2_b32 v[138:139], v176 offset0:23 offset1:54
	ds_read2_b32 v[140:141], v177 offset0:23 offset1:54
	ds_read2_b32 v[142:143], v197 offset0:23 offset1:54
	ds_read2_b32 v[144:145], v198 offset0:23 offset1:54
	ds_read2_b32 v[160:161], v199 offset0:23 offset1:54
	ds_read2_b32 v[162:163], v200 offset0:23 offset1:54
	ds_read2_b32 v[164:165], v201 offset0:23 offset1:54
	ds_read2_b32 v[166:167], v202 offset0:23 offset1:54
	s_nop 0
	s_nop 0
	v_lshl_add_u64 v[10:11], v[84:85], 0, s[44:45]
	v_mad_u64_u32 v[14:15], s[12:13], v10, s75, v[86:87]
	v_mov_b32_e32 v10, v15
	v_mad_u64_u32 v[10:11], s[12:13], v11, s75, v[10:11]
	v_mov_b32_e32 v15, v10
	v_lshl_add_u64 v[10:11], v[14:15], 0, v[76:77]
	v_lshl_add_u64 v[10:11], v[10:11], 0, v[12:13]
	s_nop 0
	s_nop 0
	v_lshl_add_u64 v[10:11], v[82:83], 0, s[42:43]
	v_mad_u64_u32 v[14:15], s[12:13], v10, s75, v[86:87]
	v_mov_b32_e32 v10, v15
	v_mad_u64_u32 v[10:11], s[12:13], v11, s75, v[10:11]
	v_mov_b32_e32 v15, v10
	v_lshl_add_u64 v[10:11], v[14:15], 0, v[76:77]
	v_lshl_add_u64 v[10:11], v[10:11], 0, v[12:13]
	s_nop 0
	s_nop 0
	v_lshl_add_u64 v[10:11], v[84:85], 0, s[42:43]
	v_mad_u64_u32 v[14:15], s[12:13], v10, s75, v[86:87]
	v_mov_b32_e32 v10, v15
	v_mad_u64_u32 v[10:11], s[12:13], v11, s75, v[10:11]
	v_mov_b32_e32 v15, v10
	v_lshl_add_u64 v[10:11], v[14:15], 0, v[76:77]
	v_lshl_add_u64 v[10:11], v[10:11], 0, v[12:13]
	s_nop 0
	global_load_dwordx4 v[126:129], v[10:11], off offset:3136
	v_lshl_add_u64 v[10:11], v[82:83], 0, s[40:41]
	v_mad_u64_u32 v[14:15], s[12:13], v10, s75, v[86:87]
	v_mov_b32_e32 v10, v15
	v_mad_u64_u32 v[10:11], s[12:13], v11, s75, v[10:11]
	v_mov_b32_e32 v15, v10
	v_lshl_add_u64 v[10:11], v[14:15], 0, v[76:77]
	v_lshl_add_u64 v[10:11], v[10:11], 0, v[12:13]
	global_load_dwordx4 v[130:133], v[10:11], off offset:3072
	global_load_dwordx4 v[34:37], v[10:11], off offset:3136
	v_lshl_add_u64 v[10:11], v[84:85], 0, s[40:41]
	v_mad_u64_u32 v[14:15], s[12:13], v10, s75, v[86:87]
	v_mov_b32_e32 v10, v15
	v_mad_u64_u32 v[10:11], s[12:13], v11, s75, v[10:11]
	v_mov_b32_e32 v15, v10
	v_lshl_add_u64 v[10:11], v[14:15], 0, v[76:77]
	v_lshl_add_u64 v[10:11], v[10:11], 0, v[12:13]
	global_load_dwordx4 v[30:33], v[10:11], off offset:3072
	global_load_dwordx4 v[26:29], v[10:11], off offset:3136
	v_lshl_add_u64 v[10:11], v[82:83], 0, s[24:25]
	v_mad_u64_u32 v[14:15], s[12:13], v10, s75, v[86:87]
	v_mov_b32_e32 v10, v15
	v_mad_u64_u32 v[10:11], s[12:13], v11, s75, v[10:11]
	v_mov_b32_e32 v15, v10
	v_lshl_add_u64 v[10:11], v[14:15], 0, v[76:77]
	v_lshl_add_u64 v[10:11], v[10:11], 0, v[12:13]
	global_load_dwordx4 v[22:25], v[10:11], off offset:3072
	global_load_dwordx4 v[18:21], v[10:11], off offset:3136
	v_lshl_add_u64 v[10:11], v[84:85], 0, s[24:25]
	v_mad_u64_u32 v[14:15], s[12:13], v10, s75, v[86:87]
	v_mov_b32_e32 v10, v15
	v_mad_u64_u32 v[10:11], s[12:13], v11, s75, v[10:11]
	v_mov_b32_e32 v15, v10
	v_sub_u32_e64 v82, v91, 8 clamp
	v_lshl_add_u64 v[10:11], v[14:15], 0, v[76:77]
	v_min_u32_e32 v82, 48, v82
	v_lshl_add_u64 v[10:11], v[10:11], 0, v[12:13]
	v_sub_u32_e32 v84, v171, v82
	global_load_dwordx4 v[14:17], v[10:11], off offset:3072
	s_nop 0
	global_load_dwordx4 v[10:13], v[10:11], off offset:3136
	v_cmp_gt_u32_e64 s[46:47], 16, v84
	v_sub_u32_e32 v84, v172, v82
	v_sub_u32_e32 v83, v168, v82
	v_cmp_gt_u32_e64 s[42:43], 16, v84
	v_sub_u32_e32 v84, v169, v82
	v_cmp_gt_u32_e32 vcc, 16, v83
	v_sub_u32_e32 v83, v170, v82
	s_waitcnt lgkmcnt(11)
; #define MFMA16(a, b, c) __builtin_amdgcn_mfma_f32_16x16x32_bf16(a, b, c, 0, 0, 0)
; __device__ __forceinline__ void na2_task(const Params& p_, int l, int task, unsigned char* lds) {
;     ...
;             for (int i = 0; i < 8; ++i) { const int a = 4 + i / 2, ci = i % 2;
;                 const size_t ktok = (size_t)b * SEQ + (row_start + a) * 64 + kst + 16 * ci + fr;
; #pragma unroll
;                 for (int ks = 0; ks < 2; ++ks) kfr[i][ks] = *(const bf16x8v*)(Z + ktok * DIN + 3 * DG + h * 64 + 32 * ks + 8 * fq); }
;             asm volatile("" ::: "memory");
;     ...
; #pragma unroll
;         for (int i = 0; i < 8; ++i) { const int a = 4 * hf + i / 2, ci = i % 2, kt = a * 2 + ci;
;             f32x4 acc = {0.f, 0.f, 0.f, 0.f};
; #pragma unroll
;             for (int ks = 0; ks < 2; ++ks) acc = MFMA16(kfr[i][ks], qf[ks], acc);
;             const int dr = row_start + a - rq;
; #pragma unroll
;             for (int r = 0; r < 4; ++r) { const int kc = kst + 16 * ci + 4 * fq + r, rel = kc - col_start, dc = kc - c;
;                 float v = acc[r] * 0.125f + bi[(dr + 7) * 31 + min(max(dc + 15, 0), 30)];
;                 v = (rel >= 0 && rel < 16) ? v : -1e30f; sc[kt][r] = v; mx = fmaxf(mx, v); } }
	v_fmamk_f32 v58, v58, 0x3e000000, v88
	v_cmp_gt_u32_e64 s[44:45], 16, v84
	v_fmamk_f32 v66, v94, 0x3e000000, v66
	v_fmamk_f32 v68, v95, 0x3e000000, v68
	v_cmp_gt_u32_e64 s[40:41], 16, v83
	v_cndmask_b32_e64 v84, v194, v58, s[44:45]
	v_sub_u32_e32 v58, v173, v82
	v_cndmask_b32_e32 v66, v194, v66, vcc
	v_cndmask_b32_e64 v68, v194, v68, s[40:41]
	s_mov_b32 s9, 0xf149f2ca
	v_fmamk_f32 v70, v96, 0x3e000000, v70
	v_fmamk_f32 v72, v97, 0x3e000000, v72
	s_waitcnt lgkmcnt(10)
	v_fmamk_f32 v59, v59, 0x3e000000, v92
	v_cmp_gt_u32_e64 s[48:49], 16, v58
	v_max3_f32 v83, v66, s9, v68
	v_cndmask_b32_e64 v70, v194, v70, s[46:47]
	v_cndmask_b32_e64 v72, v194, v72, s[42:43]
	v_cndmask_b32_e64 v85, v194, v59, s[48:49]
	v_sub_u32_e32 v59, v174, v82
	v_max3_f32 v83, v83, v70, v72
	s_waitcnt lgkmcnt(9)
	v_fmamk_f32 v60, v60, 0x3e000000, v134
	v_cmp_gt_u32_e64 s[50:51], 16, v59
	v_sub_u32_e32 v59, v175, v82
	v_max3_f32 v58, v83, v84, v85
	v_cndmask_b32_e64 v83, v194, v60, s[50:51]
	s_waitcnt lgkmcnt(8)
	v_fmamk_f32 v60, v61, 0x3e000000, v136
	v_cmp_gt_u32_e64 s[52:53], 16, v59
	v_fmac_f32_e32 v67, 0x3e000000, v62
	v_fmac_f32_e32 v69, 0x3e000000, v63
	v_cndmask_b32_e64 v82, v194, v60, s[52:53]
	v_fmac_f32_e32 v93, 0x3e000000, v39
	s_waitcnt lgkmcnt(7)
	v_fmamk_f32 v39, v42, 0x3e000000, v138
	v_max3_f32 v58, v58, v83, v82
	v_cndmask_b32_e32 v62, v194, v67, vcc
	v_cndmask_b32_e64 v63, v194, v69, s[40:41]
	v_fmac_f32_e32 v71, 0x3e000000, v64
	v_fmac_f32_e32 v73, 0x3e000000, v65
	v_fmac_f32_e32 v89, 0x3e000000, v38
	v_cndmask_b32_e32 v88, v194, v39, vcc
	s_waitcnt lgkmcnt(6)
	v_fmamk_f32 v39, v43, 0x3e000000, v140
	v_max3_f32 v58, v58, v62, v63
	v_cndmask_b32_e64 v67, v194, v71, s[46:47]
	v_cndmask_b32_e64 v69, v194, v73, s[42:43]
	v_cndmask_b32_e64 v71, v194, v89, s[44:45]
	v_cndmask_b32_e64 v89, v194, v39, s[40:41]
	s_waitcnt lgkmcnt(5)
	v_fmamk_f32 v39, v44, 0x3e000000, v142
	v_max3_f32 v58, v58, v67, v69
	v_cndmask_b32_e64 v73, v194, v93, s[48:49]
	v_fmac_f32_e32 v135, 0x3e000000, v40
	v_fmac_f32_e32 v137, 0x3e000000, v41
	v_cndmask_b32_e64 v91, v194, v39, s[46:47]
	s_waitcnt lgkmcnt(4)
	v_fmamk_f32 v39, v45, 0x3e000000, v144
	v_max3_f32 v38, v58, v71, v73
	v_cndmask_b32_e64 v86, v194, v135, s[50:51]
	v_cndmask_b32_e64 v87, v194, v137, s[52:53]
	v_cndmask_b32_e64 v92, v194, v39, s[42:43]
	s_waitcnt lgkmcnt(3)
	v_fmamk_f32 v39, v46, 0x3e000000, v160
	v_max3_f32 v38, v38, v86, v87
	v_cndmask_b32_e64 v93, v194, v39, s[44:45]
	s_waitcnt lgkmcnt(2)
	v_fmamk_f32 v39, v47, 0x3e000000, v162
	v_max3_f32 v38, v38, v88, v89
	v_cndmask_b32_e64 v94, v194, v39, s[48:49]
	s_waitcnt lgkmcnt(1)
	v_fmamk_f32 v39, v48, 0x3e000000, v164
	v_max3_f32 v38, v38, v91, v92
	v_cndmask_b32_e64 v95, v194, v39, s[50:51]
	s_waitcnt lgkmcnt(0)
	v_fmamk_f32 v39, v49, 0x3e000000, v166
	v_max3_f32 v38, v38, v93, v94
	v_cndmask_b32_e64 v96, v194, v39, s[52:53]
	v_fmac_f32_e32 v139, 0x3e000000, v54
	v_fmac_f32_e32 v141, 0x3e000000, v55
	v_max3_f32 v38, v38, v95, v96
	v_cndmask_b32_e32 v97, v194, v139, vcc
	v_cndmask_b32_e64 v134, v194, v141, s[40:41]
	v_fmac_f32_e32 v143, 0x3e000000, v56
	v_fmac_f32_e32 v145, 0x3e000000, v57
	v_max3_f32 v38, v38, v97, v134
	v_cndmask_b32_e64 v135, v194, v143, s[46:47]
	v_cndmask_b32_e64 v136, v194, v145, s[42:43]
	v_fmac_f32_e32 v161, 0x3e000000, v50
	v_fmac_f32_e32 v163, 0x3e000000, v51
	v_max3_f32 v38, v38, v135, v136
	v_cndmask_b32_e64 v137, v194, v161, s[44:45]
	v_cndmask_b32_e64 v138, v194, v163, s[48:49]
	v_max3_f32 v42, v38, v137, v138
	s_waitcnt vmcnt(0)
	ds_bpermute_b32 v98, v251, v210
	ds_bpermute_b32 v99, v251, v211
	ds_bpermute_b32 v100, v251, v212
	ds_bpermute_b32 v101, v251, v213
	ds_bpermute_b32 v102, v251, v214
	ds_bpermute_b32 v103, v251, v215
	ds_bpermute_b32 v104, v251, v216
	ds_bpermute_b32 v105, v251, v217
	ds_bpermute_b32 v106, v251, v218
	ds_bpermute_b32 v107, v251, v219
	ds_bpermute_b32 v108, v251, v220
	ds_bpermute_b32 v109, v251, v221
	ds_bpermute_b32 v110, v251, v222
	ds_bpermute_b32 v111, v251, v223
	ds_bpermute_b32 v112, v251, v224
	ds_bpermute_b32 v113, v251, v225
	ds_bpermute_b32 v114, v251, v226
	ds_bpermute_b32 v115, v251, v227
	ds_bpermute_b32 v116, v251, v228
	ds_bpermute_b32 v117, v251, v229
	ds_bpermute_b32 v118, v251, v230
	ds_bpermute_b32 v119, v251, v231
	ds_bpermute_b32 v120, v251, v232
	ds_bpermute_b32 v121, v251, v233
	ds_bpermute_b32 v122, v251, v234
	ds_bpermute_b32 v123, v251, v235
	ds_bpermute_b32 v124, v251, v236
	ds_bpermute_b32 v125, v251, v237
	ds_bpermute_b32 v126, v251, v126
	ds_bpermute_b32 v127, v251, v127
	ds_bpermute_b32 v128, v251, v128
	ds_bpermute_b32 v129, v251, v129
	ds_bpermute_b32 v130, v251, v130
	ds_bpermute_b32 v131, v251, v131
	ds_bpermute_b32 v132, v251, v132
	ds_bpermute_b32 v133, v251, v133
	ds_bpermute_b32 v34, v251, v34
	ds_bpermute_b32 v35, v251, v35
	ds_bpermute_b32 v36, v251, v36
	ds_bpermute_b32 v37, v251, v37
	ds_bpermute_b32 v30, v251, v30
	ds_bpermute_b32 v31, v251, v31
	ds_bpermute_b32 v32, v251, v32
	ds_bpermute_b32 v33, v251, v33
	ds_bpermute_b32 v26, v251, v26
	ds_bpermute_b32 v27, v251, v27
	ds_bpermute_b32 v28, v251, v28
	ds_bpermute_b32 v29, v251, v29
	ds_bpermute_b32 v22, v251, v22
	ds_bpermute_b32 v23, v251, v23
	ds_bpermute_b32 v24, v251, v24
	ds_bpermute_b32 v25, v251, v25
	ds_bpermute_b32 v18, v251, v18
	ds_bpermute_b32 v19, v251, v19
	ds_bpermute_b32 v20, v251, v20
	ds_bpermute_b32 v21, v251, v21
	ds_bpermute_b32 v14, v251, v14
	ds_bpermute_b32 v15, v251, v15
	ds_bpermute_b32 v16, v251, v16
	ds_bpermute_b32 v17, v251, v17
	ds_bpermute_b32 v10, v251, v10
	ds_bpermute_b32 v11, v251, v11
	ds_bpermute_b32 v12, v251, v12
	ds_bpermute_b32 v13, v251, v13
	s_waitcnt lgkmcnt(0)
; #define MFMA16(a, b, c) __builtin_amdgcn_mfma_f32_16x16x32_bf16(a, b, c, 0, 0, 0)
; __device__ __forceinline__ void na2_task(const Params& p_, int l, int task, unsigned char* lds) {
;     ...
; #pragma unroll
;         for (int i = 0; i < 8; ++i) { const int a = 4 * hf + i / 2, ci = i % 2, kt = a * 2 + ci;
;             f32x4 acc = {0.f, 0.f, 0.f, 0.f};
; #pragma unroll
;             for (int ks = 0; ks < 2; ++ks) acc = MFMA16(kfr[i][ks], qf[ks], acc);
;             const int dr = row_start + a - rq;
; #pragma unroll
;             for (int r = 0; r < 4; ++r) { const int kc = kst + 16 * ci + 4 * fq + r, rel = kc - col_start, dc = kc - c;
;                 float v = acc[r] * 0.125f + bi[(dr + 7) * 31 + min(max(dc + 15, 0), 30)];
;                 v = (rel >= 0 && rel < 16) ? v : -1e30f; sc[kt][r] = v; mx = fmaxf(mx, v); } }
;     }
;     mx = fmaxf(mx, __shfl_xor(mx, 16)); mx = fmaxf(mx, __shfl_xor(mx, 32));
	v_mfma_f32_16x16x32_bf16 v[38:41], v[98:101], v[6:9], 0
	ds_read2_b32 v[46:47], v176 offset0:85 offset1:116
	ds_read2_b32 v[48:49], v177 offset0:85 offset1:116
	ds_read2_b32 v[50:51], v197 offset0:85 offset1:116
	s_waitcnt vmcnt(14)
	v_mfma_f32_16x16x32_bf16 v[38:41], v[102:105], v[2:5], v[38:41]
	v_fmac_f32_e32 v165, 0x3e000000, v52
	v_fmac_f32_e32 v167, 0x3e000000, v53
	ds_read2_b32 v[52:53], v198 offset0:85 offset1:116
	ds_read2_b32 v[54:55], v199 offset0:85 offset1:116
	ds_read2_b32 v[56:57], v200 offset0:85 offset1:116
	s_waitcnt lgkmcnt(5)
	s_nop 1
	v_fmamk_f32 v38, v38, 0x3e000000, v46
	v_cndmask_b32_e32 v98, v194, v38, vcc
	s_waitcnt lgkmcnt(4)
	v_fmamk_f32 v38, v39, 0x3e000000, v48
	v_cndmask_b32_e64 v48, v194, v38, s[40:41]
	s_waitcnt lgkmcnt(3)
	v_fmamk_f32 v38, v40, 0x3e000000, v50
	v_cndmask_b32_e64 v50, v194, v38, s[46:47]
	s_waitcnt lgkmcnt(2)
	v_fmamk_f32 v38, v41, 0x3e000000, v52
	v_cndmask_b32_e64 v52, v194, v38, s[42:43]
	s_waitcnt vmcnt(13)
	v_mfma_f32_16x16x32_bf16 v[38:41], v[106:109], v[6:9], 0
	v_cndmask_b32_e64 v139, v194, v165, s[50:51]
	v_cndmask_b32_e64 v140, v194, v167, s[52:53]
	ds_read2_b32 v[58:59], v201 offset0:85 offset1:116
	s_waitcnt vmcnt(12)
	v_mfma_f32_16x16x32_bf16 v[38:41], v[110:113], v[2:5], v[38:41]
	v_max3_f32 v42, v42, v139, v140
	ds_read2_b32 v[60:61], v202 offset0:85 offset1:116
	v_max3_f32 v42, v42, v98, v48
	v_max3_f32 v42, v42, v50, v52
	s_waitcnt vmcnt(5)
	v_mfma_f32_16x16x32_bf16 v[30:33], v[30:33], v[6:9], 0
	s_waitcnt lgkmcnt(3)
	s_nop 0
	v_fmamk_f32 v38, v38, 0x3e000000, v54
	v_cndmask_b32_e64 v54, v194, v38, s[44:45]
	s_waitcnt lgkmcnt(2)
	v_fmamk_f32 v38, v39, 0x3e000000, v56
	v_cndmask_b32_e64 v99, v194, v38, s[48:49]
	v_max3_f32 v38, v42, v54, v99
	v_mfma_f32_16x16x32_bf16 v[42:45], v[114:117], v[6:9], 0
	s_waitcnt lgkmcnt(1)
	v_fmamk_f32 v39, v40, 0x3e000000, v58
	v_cndmask_b32_e64 v100, v194, v39, s[50:51]
	s_waitcnt lgkmcnt(0)
	v_fmamk_f32 v39, v41, 0x3e000000, v60
	v_cndmask_b32_e64 v101, v194, v39, s[52:53]
	v_max3_f32 v46, v38, v100, v101
	v_mfma_f32_16x16x32_bf16 v[38:41], v[118:121], v[2:5], v[42:45]
	v_lshl_add_u64 v[78:79], v[78:79], 0, v[0:1]
	s_mov_b32 s9, 0x12d20000
	v_mfma_f32_16x16x32_bf16 v[42:45], v[122:125], v[6:9], 0
	s_waitcnt vmcnt(4)
	v_mfma_f32_16x16x32_bf16 v[26:29], v[26:29], v[2:5], v[30:33]
	s_nop 2
	v_fmac_f32_e32 v47, 0x3e000000, v38
	v_fmac_f32_e32 v49, 0x3e000000, v39
	v_cndmask_b32_e32 v102, v194, v47, vcc
	v_cndmask_b32_e64 v49, v194, v49, s[40:41]
	v_fmac_f32_e32 v51, 0x3e000000, v40
	v_fmac_f32_e32 v53, 0x3e000000, v41
	v_max3_f32 v38, v46, v102, v49
	v_cndmask_b32_e64 v51, v194, v51, s[46:47]
	v_cndmask_b32_e64 v53, v194, v53, s[42:43]
	v_max3_f32 v46, v38, v51, v53
	v_mfma_f32_16x16x32_bf16 v[38:41], v[126:129], v[2:5], v[42:45]
	s_waitcnt vmcnt(3)
	v_mfma_f32_16x16x32_bf16 v[22:25], v[22:25], v[6:9], 0
	s_waitcnt vmcnt(2)
	v_mfma_f32_16x16x32_bf16 v[18:21], v[18:21], v[2:5], v[22:25]
	s_nop 3
	v_fmac_f32_e32 v55, 0x3e000000, v38
	v_fmac_f32_e32 v57, 0x3e000000, v39
	v_fmac_f32_e32 v59, 0x3e000000, v40
	v_fmac_f32_e32 v61, 0x3e000000, v41
	v_mfma_f32_16x16x32_bf16 v[38:41], v[130:133], v[6:9], 0
	v_cndmask_b32_e64 v55, v194, v55, s[44:45]
	v_cndmask_b32_e64 v103, v194, v57, s[48:49]
	v_max3_f32 v42, v46, v55, v103
	v_cndmask_b32_e64 v104, v194, v59, s[50:51]
	v_cndmask_b32_e64 v105, v194, v61, s[52:53]
	v_max3_f32 v46, v42, v104, v105
	ds_read2_b32 v[42:43], v176 offset0:147 offset1:178
	ds_read2_b32 v[44:45], v177 offset0:147 offset1:178
	v_mfma_f32_16x16x32_bf16 v[34:37], v[34:37], v[2:5], v[38:41]
	s_waitcnt lgkmcnt(1)
	v_fmac_f32_e32 v43, 0x3e000000, v18
	s_nop 0
	ds_read2_b32 v[38:39], v197 offset0:147 offset1:178
	s_waitcnt vmcnt(1)
	v_mfma_f32_16x16x32_bf16 v[6:9], v[14:17], v[6:9], 0
	s_nop 1
	v_fmamk_f32 v34, v34, 0x3e000000, v42
	v_cndmask_b32_e32 v42, v194, v34, vcc
	s_waitcnt lgkmcnt(1)
	v_fmamk_f32 v40, v35, 0x3e000000, v44
	ds_read2_b32 v[34:35], v198 offset0:147 offset1:178
	v_cndmask_b32_e64 v44, v194, v40, s[40:41]
	s_waitcnt lgkmcnt(1)
	v_fmamk_f32 v36, v36, 0x3e000000, v38
	v_max3_f32 v40, v46, v42, v44
	v_cndmask_b32_e64 v38, v194, v36, s[46:47]
	s_waitcnt lgkmcnt(0)
	v_fmamk_f32 v34, v37, 0x3e000000, v34
	v_cndmask_b32_e64 v34, v194, v34, s[42:43]
	v_max3_f32 v46, v40, v38, v34
	ds_read2_b32 v[36:37], v199 offset0:147 offset1:178
	ds_read2_b32 v[40:41], v200 offset0:147 offset1:178
	ds_read2_b32 v[30:31], v201 offset0:147 offset1:178
	s_waitcnt vmcnt(0)
	v_mfma_f32_16x16x32_bf16 v[2:5], v[10:13], v[2:5], v[6:9]
	v_fmac_f32_e32 v45, 0x3e000000, v19
	s_waitcnt lgkmcnt(2)
	v_fmamk_f32 v26, v26, 0x3e000000, v36
	v_cndmask_b32_e64 v36, v194, v26, s[44:45]
	s_waitcnt lgkmcnt(1)
	v_fmamk_f32 v26, v27, 0x3e000000, v40
	v_cndmask_b32_e64 v40, v194, v26, s[48:49]
	ds_read2_b32 v[26:27], v202 offset0:147 offset1:178
	s_waitcnt lgkmcnt(1)
	v_fmamk_f32 v28, v28, 0x3e000000, v30
	v_max3_f32 v32, v46, v36, v40
	v_cndmask_b32_e64 v106, v194, v28, s[50:51]
	v_cndmask_b32_e32 v43, v194, v43, vcc
	s_waitcnt lgkmcnt(0)
	v_fmamk_f32 v26, v29, 0x3e000000, v26
	v_cndmask_b32_e64 v107, v194, v26, s[52:53]
	v_max3_f32 v26, v32, v106, v107
	v_cndmask_b32_e64 v45, v194, v45, s[40:41]
	v_fmac_f32_e32 v39, 0x3e000000, v20
	v_fmac_f32_e32 v35, 0x3e000000, v21
	v_fmac_f32_e32 v31, 0x3e000000, v4
	v_and_b32_e32 v4, 64, v178
	v_max3_f32 v18, v26, v43, v45
	v_cndmask_b32_e64 v39, v194, v39, s[46:47]
	v_cndmask_b32_e64 v108, v194, v35, s[42:43]
	v_fmac_f32_e32 v37, 0x3e000000, v2
	v_fmac_f32_e32 v41, 0x3e000000, v3
	v_xor_b32_e32 v3, 16, v178
	v_add_u32_e32 v4, 64, v4
	v_max3_f32 v14, v18, v39, v108
	v_cndmask_b32_e64 v109, v194, v37, s[44:45]
	v_cndmask_b32_e64 v41, v194, v41, s[48:49]
	v_fmac_f32_e32 v27, 0x3e000000, v5
	v_cmp_lt_i32_e32 vcc, v3, v4
	v_max3_f32 v2, v14, v109, v41
	v_cndmask_b32_e64 v110, v194, v31, s[50:51]
	v_cndmask_b32_e64 v111, v194, v27, s[52:53]
	v_cndmask_b32_e32 v3, v178, v3, vcc
	v_max3_f32 v2, v2, v110, v111
	v_lshlrev_b32_e32 v112, 2, v3
	ds_bpermute_b32 v3, v112, v2
	s_waitcnt lgkmcnt(0)
; __device__ __forceinline__ unsigned pk2(float lo, float hi) { return f2bf(lo) | (f2bf(hi) << 16); }
; __device__ __forceinline__ void na2_task(const Params& p_, int l, int task, unsigned char* lds) {
;     ...
;     mx = fmaxf(mx, __shfl_xor(mx, 16)); mx = fmaxf(mx, __shfl_xor(mx, 32));
;     float sum = 0.f; unsigned pp[16][2];
; #pragma unroll
;     for (int kt = 0; kt < 16; ++kt) { const float e0 = __expf(sc[kt][0] - mx), e1 = __expf(sc[kt][1] - mx), e2 = __expf(sc[kt][2] - mx), e3 = __expf(sc[kt][3] - mx);
;         sum += (e0 + e1) + (e2 + e3); pp[kt][0] = pk2(e0, e1); pp[kt][1] = pk2(e2, e3); }
;     sum += __shfl_xor(sum, 16); sum += __shfl_xor(sum, 32);
	v_max_f32_e32 v3, v3, v3
	v_max_f32_e32 v2, v2, v3
	v_xor_b32_e32 v3, 32, v178
	v_cmp_lt_i32_e32 vcc, v3, v4
	s_nop 1
	v_cndmask_b32_e32 v3, v178, v3, vcc
	v_lshlrev_b32_e32 v113, 2, v3
	ds_bpermute_b32 v3, v113, v2
	s_waitcnt lgkmcnt(0)
	v_max_f32_e32 v3, v3, v3
	v_max_f32_e32 v114, v2, v3
	v_sub_f32_e32 v6, v84, v114
	v_mul_f32_e32 v6, 0x3fb8aa3b, v6
	v_sub_f32_e32 v3, v68, v114
	v_exp_f32_e32 v60, v6
	v_sub_f32_e32 v6, v85, v114
	v_mul_f32_e32 v3, 0x3fb8aa3b, v3
	v_mul_f32_e32 v6, 0x3fb8aa3b, v6
	v_sub_f32_e32 v2, v66, v114
	v_exp_f32_e32 v4, v3
	v_sub_f32_e32 v3, v70, v114
	v_sub_f32_e32 v5, v72, v114
	v_exp_f32_e32 v64, v6
	v_sub_f32_e32 v6, v83, v114
	v_mul_f32_e32 v2, 0x3fb8aa3b, v2
	v_mul_f32_e32 v3, 0x3fb8aa3b, v3
	v_mul_f32_e32 v5, 0x3fb8aa3b, v5
	v_mul_f32_e32 v6, 0x3fb8aa3b, v6
	v_exp_f32_e32 v2, v2
	v_exp_f32_e32 v3, v3
	v_exp_f32_e32 v5, v5
	v_exp_f32_e32 v61, v6
	v_sub_f32_e32 v6, v82, v114
	v_mul_f32_e32 v6, 0x3fb8aa3b, v6
	v_exp_f32_e32 v65, v6
	v_pk_add_f32 v[6:7], v[2:3], v[4:5]
	v_sub_f32_e32 v8, v87, v114
	v_add_f32_e32 v6, v6, v7
	v_add_f32_e32 v9, 0, v6
	v_pk_add_f32 v[6:7], v[60:61], v[64:65]
	v_mul_f32_e32 v8, 0x3fb8aa3b, v8
	v_pk_add_f32 v[6:7], v[6:7], v[6:7] op_sel_hi:[0,1]
	v_sub_f32_e32 v6, v62, v114
	v_mul_f32_e32 v6, 0x3fb8aa3b, v6
	v_exp_f32_e32 v84, v6
	v_sub_f32_e32 v6, v63, v114
	v_mul_f32_e32 v6, 0x3fb8aa3b, v6
	v_exp_f32_e32 v85, v6
	v_sub_f32_e32 v6, v67, v114
	v_mul_f32_e32 v6, 0x3fb8aa3b, v6
	v_exp_f32_e32 v115, v6
	v_sub_f32_e32 v6, v69, v114
	v_mul_f32_e32 v6, 0x3fb8aa3b, v6
	v_exp_f32_e32 v116, v6
	v_sub_f32_e32 v6, v71, v114
	v_mul_f32_e32 v6, 0x3fb8aa3b, v6
	v_exp_f32_e32 v12, v6
	v_sub_f32_e32 v6, v73, v114
	v_mul_f32_e32 v6, 0x3fb8aa3b, v6
	v_exp_f32_e32 v62, v6
	v_sub_f32_e32 v6, v86, v114
	v_mul_f32_e32 v6, 0x3fb8aa3b, v6
	v_exp_f32_e32 v6, v6
	v_exp_f32_e32 v8, v8
	v_add_f32_e32 v13, v84, v85
	v_add_f32_e32 v63, v115, v116
	v_pk_add_f32 v[10:11], v[12:13], v[62:63]
	v_pk_add_f32 v[14:15], v[6:7], v[8:9]
	v_sub_f32_e32 v7, v88, v114
	v_pk_add_f32 v[10:11], v[10:11], v[14:15]
	v_mul_f32_e32 v7, 0x3fb8aa3b, v7
	v_pk_add_f32 v[14:15], v[10:11], v[10:11] op_sel_hi:[0,1]
	v_exp_f32_e32 v10, v7
	v_sub_f32_e32 v7, v89, v114
	v_mul_f32_e32 v7, 0x3fb8aa3b, v7
	v_exp_f32_e32 v58, v7
	v_sub_f32_e32 v7, v91, v114
	v_mul_f32_e32 v7, 0x3fb8aa3b, v7
	v_exp_f32_e32 v11, v7
	v_sub_f32_e32 v7, v92, v114
	v_mul_f32_e32 v7, 0x3fb8aa3b, v7
	v_exp_f32_e32 v59, v7
	v_sub_f32_e32 v7, v93, v114
	v_mul_f32_e32 v7, 0x3fb8aa3b, v7
	v_exp_f32_e32 v13, v7
	v_sub_f32_e32 v7, v94, v114
	v_mul_f32_e32 v7, 0x3fb8aa3b, v7
	v_exp_f32_e32 v86, v7
	v_sub_f32_e32 v7, v95, v114
	v_mul_f32_e32 v7, 0x3fb8aa3b, v7
	v_exp_f32_e32 v87, v7
	v_sub_f32_e32 v7, v96, v114
	v_mul_f32_e32 v7, 0x3fb8aa3b, v7
	v_exp_f32_e32 v88, v7
	v_sub_f32_e32 v7, v97, v114
	v_pk_add_f32 v[16:17], v[10:11], v[58:59]
	v_mul_f32_e32 v7, 0x3fb8aa3b, v7
	v_pk_add_f32 v[18:19], v[16:17], v[16:17] op_sel_hi:[0,1]
	v_exp_f32_e32 v16, v7
	v_sub_f32_e32 v7, v134, v114
	v_mul_f32_e32 v7, 0x3fb8aa3b, v7
	v_exp_f32_e32 v20, v7
	v_sub_f32_e32 v7, v135, v114
	v_mul_f32_e32 v7, 0x3fb8aa3b, v7
	v_exp_f32_e32 v18, v7
	v_sub_f32_e32 v7, v136, v114
	v_mul_f32_e32 v7, 0x3fb8aa3b, v7
	v_exp_f32_e32 v14, v7
	v_sub_f32_e32 v7, v137, v114
	v_mul_f32_e32 v7, 0x3fb8aa3b, v7
	v_exp_f32_e32 v68, v7
	v_sub_f32_e32 v7, v138, v114
	v_mul_f32_e32 v7, 0x3fb8aa3b, v7
	v_exp_f32_e32 v72, v7
	v_sub_f32_e32 v7, v139, v114
	v_mul_f32_e32 v7, 0x3fb8aa3b, v7
	v_exp_f32_e32 v69, v7
	v_sub_f32_e32 v7, v140, v114
	v_mul_f32_e32 v7, 0x3fb8aa3b, v7
	v_exp_f32_e32 v73, v7
	v_sub_f32_e32 v7, v98, v114
	v_mul_f32_e32 v7, 0x3fb8aa3b, v7
	v_pk_add_f32 v[24:25], v[18:19], v[14:15]
	v_exp_f32_e32 v19, v7
	v_sub_f32_e32 v7, v48, v114
	v_add_f32_e32 v17, v13, v86
	v_add_f32_e32 v21, v87, v88
	v_mul_f32_e32 v7, 0x3fb8aa3b, v7
	v_pk_add_f32 v[22:23], v[16:17], v[20:21]
	v_exp_f32_e32 v21, v7
	v_sub_f32_e32 v7, v50, v114
	v_mul_f32_e32 v7, 0x3fb8aa3b, v7
	v_exp_f32_e32 v89, v7
	v_sub_f32_e32 v7, v52, v114
	v_mul_f32_e32 v7, 0x3fb8aa3b, v7
	v_exp_f32_e32 v91, v7
	v_sub_f32_e32 v7, v54, v114
	v_mul_f32_e32 v7, 0x3fb8aa3b, v7
	v_exp_f32_e32 v66, v7
	v_sub_f32_e32 v7, v99, v114
	v_pk_add_f32 v[22:23], v[22:23], v[24:25]
	v_mul_f32_e32 v7, 0x3fb8aa3b, v7
	v_pk_add_f32 v[56:57], v[22:23], v[22:23] op_sel_hi:[0,1]
	v_pk_add_f32 v[22:23], v[68:69], v[72:73]
	v_exp_f32_e32 v70, v7
	v_sub_f32_e32 v7, v100, v114
	v_pk_add_f32 v[46:47], v[22:23], v[22:23] op_sel_hi:[0,1]
	v_mul_f32_e32 v7, 0x3fb8aa3b, v7
	v_exp_f32_e32 v46, v7
	v_sub_f32_e32 v7, v101, v114
	v_mul_f32_e32 v7, 0x3fb8aa3b, v7
	v_exp_f32_e32 v56, v7
	v_add_f32_e32 v67, v19, v21
	v_add_f32_e32 v71, v89, v91
	v_pk_add_f32 v[22:23], v[66:67], v[70:71]
	v_pk_add_f32 v[24:25], v[46:47], v[56:57]
	v_sub_f32_e32 v7, v102, v114
	v_pk_add_f32 v[22:23], v[22:23], v[24:25]
	v_mul_f32_e32 v7, 0x3fb8aa3b, v7
	v_pk_add_f32 v[26:27], v[22:23], v[22:23] op_sel_hi:[0,1]
	v_exp_f32_e32 v22, v7
	v_sub_f32_e32 v7, v49, v114
	v_mul_f32_e32 v7, 0x3fb8aa3b, v7
	v_exp_f32_e32 v24, v7
	v_sub_f32_e32 v7, v51, v114
	v_mul_f32_e32 v7, 0x3fb8aa3b, v7
	v_exp_f32_e32 v23, v7
	v_sub_f32_e32 v7, v53, v114
	v_mul_f32_e32 v7, 0x3fb8aa3b, v7
	v_exp_f32_e32 v25, v7
	v_sub_f32_e32 v7, v55, v114
	v_mul_f32_e32 v7, 0x3fb8aa3b, v7
	v_exp_f32_e32 v67, v7
	v_sub_f32_e32 v7, v103, v114
	v_mul_f32_e32 v7, 0x3fb8aa3b, v7
	v_exp_f32_e32 v71, v7
	v_sub_f32_e32 v7, v104, v114
	v_mul_f32_e32 v7, 0x3fb8aa3b, v7
	v_exp_f32_e32 v92, v7
	v_sub_f32_e32 v7, v105, v114
	v_mul_f32_e32 v7, 0x3fb8aa3b, v7
	v_exp_f32_e32 v93, v7
	v_sub_f32_e32 v7, v42, v114
	v_pk_add_f32 v[28:29], v[22:23], v[24:25]
; __device__ __forceinline__ unsigned pk2(float lo, float hi) { return f2bf(lo) | (f2bf(hi) << 16); }
; __device__ __forceinline__ float bflo(unsigned u) { return __uint_as_float(u << 16); }
; __device__ __forceinline__ float bfhi(unsigned u) { return __uint_as_float(u & 0xffff0000u); }
; __device__ __forceinline__ float silu_f(float v) { return v / (1.f + __expf(-v)); }
; #define MFMA16(a, b, c) __builtin_amdgcn_mfma_f32_16x16x32_bf16(a, b, c, 0, 0, 0)
; __device__ __forceinline__ void na2_task(const Params& p_, int l, int task, unsigned char* lds) {
;     ...
;     float sum = 0.f; unsigned pp[16][2];
; #pragma unroll
;     for (int kt = 0; kt < 16; ++kt) { const float e0 = __expf(sc[kt][0] - mx), e1 = __expf(sc[kt][1] - mx), e2 = __expf(sc[kt][2] - mx), e3 = __expf(sc[kt][3] - mx);
;         sum += (e0 + e1) + (e2 + e3); pp[kt][0] = pk2(e0, e1); pp[kt][1] = pk2(e2, e3); }
;     sum += __shfl_xor(sum, 16); sum += __shfl_xor(sum, 32);
;     const float inv = 1.f / sum;
;     const bf16* VTh = VT + (size_t)hh * 64 * 520;
; #pragma unroll
;     for (int dt = 0; dt < 4; ++dt) { f32x4 o = {0.f, 0.f, 0.f, 0.f};
; #pragma unroll
;         for (int t = 0; t < 8; ++t) { const int k0 = 2 * t, k1 = 2 * t + 1, a0 = k0 / 2, c0 = k0 % 2, a1 = k1 / 2, c1 = k1 % 2;
;             const u32x2 vlo = *(const u32x2*)(VTh + (16 * dt + fr) * 520 + a0 * 64 + kst + 16 * c0 + 4 * fq), vhi = *(const u32x2*)(VTh + (16 * dt + fr) * 520 + a1 * 64 + kst + 16 * c1 + 4 * fq);
;             o = MFMA16(mk8(vlo.x, vlo.y, vhi.x, vhi.y), mk8(pp[k0][0], pp[k0][1], pp[k1][0], pp[k1][1]), o); }
;         const u32x2 gz = *(const u32x2*)(Z + qtok * DIN + 5 * DG + h * 64 + 16 * dt + 4 * fq); u32x2 ov;
;         ov.x = pk2(o[0] * inv * silu_f(bflo(gz.x)), o[1] * inv * silu_f(bfhi(gz.x))); ov.y = pk2(o[2] * inv * silu_f(bflo(gz.y)), o[3] * inv * silu_f(bfhi(gz.y)));
	v_mul_f32_e32 v7, 0x3fb8aa3b, v7
	v_pk_add_f32 v[30:31], v[28:29], v[28:29] op_sel_hi:[0,1]
	v_exp_f32_e32 v28, v7
	v_sub_f32_e32 v7, v44, v114
	v_mul_f32_e32 v7, 0x3fb8aa3b, v7
	v_exp_f32_e32 v32, v7
	v_sub_f32_e32 v7, v38, v114
	v_mul_f32_e32 v7, 0x3fb8aa3b, v7
	v_exp_f32_e32 v30, v7
	v_sub_f32_e32 v7, v34, v114
	v_mul_f32_e32 v7, 0x3fb8aa3b, v7
	v_exp_f32_e32 v26, v7
	v_sub_f32_e32 v7, v36, v114
	v_mul_f32_e32 v7, 0x3fb8aa3b, v7
	v_exp_f32_e32 v48, v7
	v_sub_f32_e32 v7, v40, v114
	v_mul_f32_e32 v7, 0x3fb8aa3b, v7
	v_exp_f32_e32 v52, v7
	v_sub_f32_e32 v7, v106, v114
	v_mul_f32_e32 v7, 0x3fb8aa3b, v7
	v_exp_f32_e32 v49, v7
	v_sub_f32_e32 v7, v107, v114
	v_mul_f32_e32 v7, 0x3fb8aa3b, v7
	v_exp_f32_e32 v53, v7
	v_sub_f32_e32 v7, v43, v114
	v_mul_f32_e32 v7, 0x3fb8aa3b, v7
	v_pk_add_f32 v[36:37], v[30:31], v[26:27]
	v_exp_f32_e32 v31, v7
	v_sub_f32_e32 v7, v45, v114
	v_add_f32_e32 v29, v67, v71
	v_add_f32_e32 v33, v92, v93
	v_mul_f32_e32 v7, 0x3fb8aa3b, v7
	v_pk_add_f32 v[34:35], v[28:29], v[32:33]
	v_exp_f32_e32 v33, v7
	v_sub_f32_e32 v7, v39, v114
	v_mul_f32_e32 v7, 0x3fb8aa3b, v7
	v_exp_f32_e32 v94, v7
	v_sub_f32_e32 v7, v108, v114
	v_mul_f32_e32 v7, 0x3fb8aa3b, v7
	v_exp_f32_e32 v95, v7
	v_sub_f32_e32 v7, v109, v114
	v_mul_f32_e32 v7, 0x3fb8aa3b, v7
	v_exp_f32_e32 v50, v7
	v_sub_f32_e32 v7, v41, v114
	v_pk_add_f32 v[34:35], v[34:35], v[36:37]
	v_mul_f32_e32 v7, 0x3fb8aa3b, v7
	v_pk_add_f32 v[36:37], v[34:35], v[34:35] op_sel_hi:[0,1]
	v_pk_add_f32 v[34:35], v[48:49], v[52:53]
	v_exp_f32_e32 v54, v7
	v_sub_f32_e32 v7, v110, v114
	v_pk_add_f32 v[34:35], v[34:35], v[34:35] op_sel_hi:[0,1]
	v_mul_f32_e32 v7, 0x3fb8aa3b, v7
	v_exp_f32_e32 v34, v7
	v_sub_f32_e32 v7, v111, v114
	v_mul_f32_e32 v7, 0x3fb8aa3b, v7
	v_exp_f32_e32 v36, v7
	v_add_f32_e32 v51, v31, v33
	v_add_f32_e32 v55, v94, v95
	v_pk_add_f32 v[38:39], v[50:51], v[54:55]
	v_pk_add_f32 v[40:41], v[34:35], v[36:37]
	v_bfe_u32 v35, v12, 16, 1
	v_pk_add_f32 v[38:39], v[38:39], v[40:41]
	v_bfe_u32 v37, v13, 16, 1
	v_add_f32_e32 v7, v38, v39
	ds_bpermute_b32 v9, v112, v7
	v_lshlrev_b64 v[38:39], 12, v[74:75]
	v_lshl_add_u64 v[38:39], s[62:63], 0, v[38:39]
	v_lshl_add_u64 v[38:39], v[38:39], 0, v[76:77]
	v_lshl_add_u64 v[42:43], v[38:39], 0, v[0:1]
	s_waitcnt lgkmcnt(0)
	v_add_f32_e32 v7, v7, v9
	ds_bpermute_b32 v9, v113, v7
	v_bfe_u32 v41, v87, 16, 1
	v_add3_u32 v41, v87, v41, s14
	v_add3_u32 v13, v13, v37, s14
	v_bfe_u32 v37, v69, 16, 1
	s_waitcnt lgkmcnt(0)
	v_add_f32_e32 v7, v7, v9
	v_div_scale_f32 v9, s[12:13], v7, v7, 1.0
	v_rcp_f32_e32 v15, v9
	v_bfe_u32 v51, v92, 16, 1
	v_add3_u32 v51, v92, v51, s14
	s_mov_b64 s[12:13], 0x1400
	v_fma_f32 v17, -v9, v15, 1.0
	v_fmac_f32_e32 v15, v17, v15
	v_div_scale_f32 v17, vcc, 1.0, v7, 1.0
	v_mul_f32_e32 v27, v17, v15
	v_fma_f32 v29, -v9, v27, v17
	v_fmac_f32_e32 v27, v29, v15
	v_fma_f32 v9, -v9, v27, v17
	v_div_fmas_f32 v9, v9, v15, v27
	v_div_fixup_f32 v40, v9, v7, 1.0
	v_lshl_add_u32 v7, v80, 1, v81
	v_mul_u32_u24_e32 v9, 0x410, v90
	v_add3_u32 v0, v7, v9, v0
	v_bfe_u32 v7, v65, 16, 1
	v_bfe_u32 v9, v64, 16, 1
	v_bfe_u32 v15, v5, 16, 1
	v_bfe_u32 v17, v4, 16, 1
	v_bfe_u32 v27, v60, 16, 1
	v_bfe_u32 v29, v61, 16, 1
	v_add3_u32 v17, v4, v17, s14
	v_add3_u32 v15, v5, v15, s14
	v_add3_u32 v4, v64, v9, s14
	v_add3_u32 v5, v65, v7, s14
	v_bfe_u32 v7, v2, 16, 1
	v_bfe_u32 v9, v3, 16, 1
	v_add3_u32 v29, v61, v29, s14
	v_add3_u32 v27, v60, v27, s14
	v_add3_u32 v3, v3, v9, s14
	v_add3_u32 v2, v2, v7, s14
	v_lshrrev_b32_e32 v7, 16, v27
	v_lshrrev_b32_e32 v9, 16, v29
	v_and_or_b32 v5, v5, s15, v9
	v_and_or_b32 v4, v4, s15, v7
	v_bfe_u32 v7, v8, 16, 1
	v_bfe_u32 v9, v62, 16, 1
	v_lshrrev_b32_e32 v3, 16, v3
	v_add3_u32 v7, v8, v7, s14
	v_add3_u32 v8, v62, v9, s14
	v_bfe_u32 v9, v6, 16, 1
	v_bfe_u32 v29, v115, 16, 1
	v_and_or_b32 v3, v15, s15, v3
	v_bfe_u32 v15, v116, 16, 1
	v_add3_u32 v6, v6, v9, s14
	v_add3_u32 v9, v12, v35, s14
	v_add3_u32 v12, v115, v29, s14
	v_add3_u32 v15, v116, v15, s14
	v_lshrrev_b32_e32 v6, 16, v6
	v_lshrrev_b32_e32 v12, 16, v12
	v_lshrrev_b32_e32 v29, 16, v9
	v_and_or_b32 v9, v7, s15, v6
	v_and_or_b32 v8, v8, s15, v29
	v_and_or_b32 v7, v15, s15, v12
	v_bfe_u32 v12, v88, 16, 1
	v_bfe_u32 v15, v86, 16, 1
	v_bfe_u32 v29, v10, 16, 1
	v_add3_u32 v15, v86, v15, s14
	v_add3_u32 v12, v88, v12, s14
	v_add3_u32 v10, v10, v29, s14
	v_lshrrev_b32_e32 v29, 16, v13
	v_lshrrev_b32_e32 v13, 16, v41
	v_and_or_b32 v13, v12, s15, v13
	v_and_or_b32 v12, v15, s15, v29
	v_bfe_u32 v15, v14, 16, 1
	v_bfe_u32 v29, v20, 16, 1
	v_add3_u32 v14, v14, v15, s14
	v_add3_u32 v20, v20, v29, s14
	v_bfe_u32 v15, v18, 16, 1
	v_bfe_u32 v29, v16, 16, 1
	v_add3_u32 v15, v18, v15, s14
	v_add3_u32 v16, v16, v29, s14
	v_lshrrev_b32_e32 v15, 16, v15
	v_lshrrev_b32_e32 v29, 16, v16
	v_and_or_b32 v15, v14, s15, v15
	v_and_or_b32 v14, v20, s15, v29
	v_bfe_u32 v29, v21, 16, 1
	v_add3_u32 v29, v21, v29, s14
	v_bfe_u32 v21, v46, 16, 1
	v_add3_u32 v21, v46, v21, s14
	v_add_co_u32_e32 v46, vcc, s74, v78
	ds_read2_b64 v[74:77], v0 offset1:4
	s_nop 0
	v_addc_co_u32_e32 v47, vcc, 0, v79, vcc
	global_load_dwordx2 v[46:47], v[46:47], off offset:1024
	ds_read2_b64 v[80:83], v0 offset0:16 offset1:20
	v_lshrrev_b32_e32 v2, 16, v2
	v_and_or_b32 v2, v17, s15, v2
	v_bfe_u32 v27, v84, 16, 1
	v_bfe_u32 v17, v85, 16, 1
	s_waitcnt lgkmcnt(1)
	v_mfma_f32_16x16x32_bf16 v[74:77], v[74:77], v[2:5], 0
	v_add3_u32 v27, v84, v27, s14
	v_add3_u32 v17, v85, v17, s14
	v_lshrrev_b32_e32 v27, 16, v27
	v_and_or_b32 v6, v17, s15, v27
	v_bfe_u32 v35, v11, 16, 1
	v_bfe_u32 v17, v59, 16, 1
	s_waitcnt lgkmcnt(0)
; __device__ __forceinline__ unsigned pk2(float lo, float hi) { return f2bf(lo) | (f2bf(hi) << 16); }
; __device__ __forceinline__ float bflo(unsigned u) { return __uint_as_float(u << 16); }
; __device__ __forceinline__ float bfhi(unsigned u) { return __uint_as_float(u & 0xffff0000u); }
; __device__ __forceinline__ float silu_f(float v) { return v / (1.f + __expf(-v)); }
; #define MFMA16(a, b, c) __builtin_amdgcn_mfma_f32_16x16x32_bf16(a, b, c, 0, 0, 0)
; __device__ __forceinline__ void na2_task(const Params& p_, int l, int task, unsigned char* lds) {
;     ...
; #pragma unroll
;     for (int dt = 0; dt < 4; ++dt) { f32x4 o = {0.f, 0.f, 0.f, 0.f};
; #pragma unroll
;         for (int t = 0; t < 8; ++t) { const int k0 = 2 * t, k1 = 2 * t + 1, a0 = k0 / 2, c0 = k0 % 2, a1 = k1 / 2, c1 = k1 % 2;
;             const u32x2 vlo = *(const u32x2*)(VTh + (16 * dt + fr) * 520 + a0 * 64 + kst + 16 * c0 + 4 * fq), vhi = *(const u32x2*)(VTh + (16 * dt + fr) * 520 + a1 * 64 + kst + 16 * c1 + 4 * fq);
;             o = MFMA16(mk8(vlo.x, vlo.y, vhi.x, vhi.y), mk8(pp[k0][0], pp[k0][1], pp[k1][0], pp[k1][1]), o); }
;         const u32x2 gz = *(const u32x2*)(Z + qtok * DIN + 5 * DG + h * 64 + 16 * dt + 4 * fq); u32x2 ov;
;         ov.x = pk2(o[0] * inv * silu_f(bflo(gz.x)), o[1] * inv * silu_f(bfhi(gz.x))); ov.y = pk2(o[2] * inv * silu_f(bflo(gz.y)), o[3] * inv * silu_f(bfhi(gz.y)));
;         *(u32x2*)(CAT + qtok * DM + 512 + h * 64 + 16 * dt + 4 * fq) = ov; }
	v_mfma_f32_16x16x32_bf16 v[60:63], v[80:83], v[6:9], v[74:77]
	v_bfe_u32 v27, v58, 16, 1
	v_add3_u32 v11, v11, v35, s14
	v_add3_u32 v27, v58, v27, s14
	ds_read2_b64 v[74:77], v0 offset0:32 offset1:36
	v_add3_u32 v17, v59, v17, s14
	v_lshrrev_b32_e32 v10, 16, v10
	v_lshrrev_b32_e32 v11, 16, v11
	v_and_or_b32 v11, v17, s15, v11
	v_and_or_b32 v10, v27, s15, v10
	v_bfe_u32 v35, v68, 16, 1
	v_bfe_u32 v17, v73, 16, 1
	s_waitcnt lgkmcnt(0)
	v_mfma_f32_16x16x32_bf16 v[58:61], v[74:77], v[10:13], v[60:63]
	v_bfe_u32 v27, v72, 16, 1
	v_add3_u32 v18, v69, v37, s14
	s_nop 0
	ds_read2_b64 v[62:65], v0 offset0:48 offset1:52
	v_add3_u32 v35, v68, v35, s14
	v_add3_u32 v27, v72, v27, s14
	v_add3_u32 v17, v73, v17, s14
	v_lshrrev_b32_e32 v16, 16, v35
	v_lshrrev_b32_e32 v18, 16, v18
	v_and_or_b32 v17, v17, s15, v18
	v_and_or_b32 v16, v27, s15, v16
	v_bfe_u32 v35, v19, 16, 1
	v_bfe_u32 v37, v89, 16, 1
	s_waitcnt lgkmcnt(0)
	v_mfma_f32_16x16x32_bf16 v[58:61], v[62:65], v[14:17], v[58:61]
	ds_read2_b64 v[62:65], v0 offset0:64 offset1:68
	v_bfe_u32 v41, v66, 16, 1
	v_bfe_u32 v18, v56, 16, 1
	v_bfe_u32 v20, v70, 16, 1
	v_bfe_u32 v27, v91, 16, 1
	v_add3_u32 v41, v66, v41, s14
	v_add3_u32 v37, v89, v37, s14
	v_add3_u32 v19, v19, v35, s14
	v_add3_u32 v18, v56, v18, s14
	v_add3_u32 v27, v91, v27, s14
	v_add3_u32 v20, v70, v20, s14
	v_lshrrev_b32_e32 v21, 16, v21
	v_lshrrev_b32_e32 v35, 16, v19
	v_lshrrev_b32_e32 v19, 16, v37
	v_lshrrev_b32_e32 v37, 16, v41
	v_and_or_b32 v21, v18, s15, v21
	v_and_or_b32 v20, v20, s15, v37
	v_and_or_b32 v19, v27, s15, v19
	v_and_or_b32 v18, v29, s15, v35
	v_bfe_u32 v27, v93, 16, 1
	v_bfe_u32 v29, v71, 16, 1
	s_waitcnt lgkmcnt(0)
	v_mfma_f32_16x16x32_bf16 v[56:59], v[62:65], v[18:21], v[58:61]
	v_bfe_u32 v35, v25, 16, 1
	v_bfe_u32 v37, v24, 16, 1
	v_add3_u32 v37, v24, v37, s14
	ds_read2_b64 v[60:63], v0 offset0:80 offset1:84
	v_add3_u32 v35, v25, v35, s14
	v_add3_u32 v24, v71, v29, s14
	v_add3_u32 v25, v93, v27, s14
	v_bfe_u32 v27, v22, 16, 1
	v_bfe_u32 v29, v23, 16, 1
	v_bfe_u32 v41, v67, 16, 1
	v_add3_u32 v41, v67, v41, s14
	v_add3_u32 v23, v23, v29, s14
	v_add3_u32 v22, v22, v27, s14
	v_lshrrev_b32_e32 v22, 16, v22
	v_lshrrev_b32_e32 v23, 16, v23
	v_lshrrev_b32_e32 v27, 16, v41
	v_lshrrev_b32_e32 v29, 16, v51
	v_and_or_b32 v25, v25, s15, v29
	v_and_or_b32 v24, v24, s15, v27
	v_and_or_b32 v23, v35, s15, v23
	v_and_or_b32 v22, v37, s15, v22
	v_bfe_u32 v27, v26, 16, 1
	v_bfe_u32 v37, v32, 16, 1
	s_waitcnt lgkmcnt(0)
	v_mfma_f32_16x16x32_bf16 v[56:59], v[60:63], v[22:25], v[56:59]
	ds_read2_b64 v[60:63], v0 offset0:96 offset1:100
	v_add3_u32 v26, v26, v27, s14
	v_add3_u32 v32, v32, v37, s14
	v_bfe_u32 v27, v30, 16, 1
	v_bfe_u32 v37, v28, 16, 1
	v_bfe_u32 v41, v48, 16, 1
	v_bfe_u32 v51, v49, 16, 1
	v_bfe_u32 v29, v53, 16, 1
	v_bfe_u32 v35, v52, 16, 1
	v_add3_u32 v27, v30, v27, s14
	v_add3_u32 v30, v49, v51, s14
	v_add3_u32 v41, v48, v41, s14
	v_add3_u32 v28, v28, v37, s14
	v_add3_u32 v35, v52, v35, s14
	v_add3_u32 v29, v53, v29, s14
	v_lshrrev_b32_e32 v27, 16, v27
	v_lshrrev_b32_e32 v37, 16, v28
	v_lshrrev_b32_e32 v28, 16, v41
	v_lshrrev_b32_e32 v30, 16, v30
	v_and_or_b32 v27, v26, s15, v27
	v_and_or_b32 v29, v29, s15, v30
	v_and_or_b32 v28, v35, s15, v28
	v_and_or_b32 v26, v32, s15, v37
	v_bfe_u32 v30, v36, 16, 1
	v_bfe_u32 v37, v33, 16, 1
	s_waitcnt lgkmcnt(0)
	v_mfma_f32_16x16x32_bf16 v[56:59], v[60:63], v[26:29], v[56:59]
	ds_read2_b64 v[60:63], v0 offset0:112 offset1:116
	v_add3_u32 v30, v36, v30, s14
	v_add3_u32 v36, v33, v37, s14
	v_bfe_u32 v33, v34, 16, 1
	v_bfe_u32 v37, v31, 16, 1
	v_bfe_u32 v41, v94, 16, 1
	v_bfe_u32 v48, v50, 16, 1
	v_bfe_u32 v32, v54, 16, 1
	v_bfe_u32 v35, v95, 16, 1
	v_add3_u32 v33, v34, v33, s14
	v_add3_u32 v34, v50, v48, s14
	v_add3_u32 v41, v94, v41, s14
	v_add3_u32 v31, v31, v37, s14
	v_add3_u32 v35, v95, v35, s14
	v_add3_u32 v32, v54, v32, s14
	v_lshrrev_b32_e32 v33, 16, v33
	v_lshrrev_b32_e32 v37, 16, v31
	v_lshrrev_b32_e32 v31, 16, v41
	v_lshrrev_b32_e32 v34, 16, v34
	v_and_or_b32 v33, v30, s15, v33
	v_and_or_b32 v32, v32, s15, v34
	v_and_or_b32 v31, v35, s15, v31
	v_and_or_b32 v30, v36, s15, v37
	s_waitcnt vmcnt(0)
	v_lshlrev_b32_e32 v41, 16, v47
	v_lshl_add_u64 v[44:45], v[78:79], 0, s[12:13]
	s_waitcnt lgkmcnt(0)
	v_mfma_f32_16x16x32_bf16 v[34:37], v[60:63], v[30:33], v[56:59]
	global_load_dwordx2 v[48:49], v[44:45], off offset:32
	global_load_dwordx2 v[50:51], v[44:45], off offset:64
	s_nop 0
	global_load_dwordx2 v[44:45], v[44:45], off offset:96
	v_lshlrev_b32_e32 v56, 16, v46
	v_mul_f32_e32 v52, 0xbfb8aa3b, v56
	v_and_b32_e32 v57, 0xffff0000, v47
	v_mul_f32_e32 v47, 0xbfb8aa3b, v41
	v_exp_f32_e32 v52, v52
	v_exp_f32_e32 v53, v47
	s_mov_b64 s[12:13], 0x12d20400
	v_lshl_add_u64 v[38:39], v[42:43], 0, s[12:13]
	v_mov_b32_e32 v54, v34
	v_pk_add_f32 v[52:53], v[52:53], 1.0 op_sel_hi:[1,0]
	v_mov_b32_e32 v55, v36
	v_div_scale_f32 v47, s[12:13], v53, v53, v41
	v_rcp_f32_e32 v59, v47
	v_and_b32_e32 v58, 0xffff0000, v46
	v_pk_mul_f32 v[54:55], v[40:41], v[54:55] op_sel_hi:[0,1]
	v_mul_f32_e32 v46, 0xbfb8aa3b, v58
	v_fma_f32 v34, -v47, v59, 1.0
	v_fmac_f32_e32 v59, v34, v59
	v_div_scale_f32 v34, vcc, v41, v53, v41
	v_mul_f32_e32 v36, v34, v59
	v_fma_f32 v60, -v47, v36, v34
	v_fmac_f32_e32 v36, v60, v59
	v_fma_f32 v34, -v47, v36, v34
	v_div_scale_f32 v47, s[12:13], v52, v52, v56
	v_rcp_f32_e32 v60, v47
	v_div_fmas_f32 v34, v34, v59, v36
	v_div_fixup_f32 v53, v34, v53, v41
	v_exp_f32_e32 v46, v46
	v_fma_f32 v34, -v47, v60, 1.0
	v_fmac_f32_e32 v60, v34, v60
	v_div_scale_f32 v34, vcc, v56, v52, v56
	v_mul_f32_e32 v36, v34, v60
	v_fma_f32 v41, -v47, v36, v34
	v_fmac_f32_e32 v36, v41, v60
	v_mul_f32_e32 v41, 0xbfb8aa3b, v57
	v_fma_f32 v34, -v47, v36, v34
	v_exp_f32_e32 v47, v41
	v_div_fmas_f32 v34, v34, v60, v36
	v_div_fixup_f32 v52, v34, v52, v56
	v_mov_b32_e32 v36, v35
	v_pk_add_f32 v[46:47], v[46:47], 1.0 op_sel_hi:[1,0]
	v_pk_mul_f32 v[64:65], v[54:55], v[52:53]
	v_div_scale_f32 v34, s[12:13], v47, v47, v57
	v_rcp_f32_e32 v41, v34
	v_div_scale_f32 v52, s[12:13], v46, v46, v58
	v_rcp_f32_e32 v56, v52
	v_fma_f32 v35, -v34, v41, 1.0
	v_pk_mul_f32 v[60:61], v[40:41], v[36:37] op_sel_hi:[0,1]
	v_fmac_f32_e32 v41, v35, v41
	v_div_scale_f32 v35, vcc, v57, v47, v57
	v_mul_f32_e32 v36, v35, v41
	v_fma_f32 v37, -v34, v36, v35
	v_fmac_f32_e32 v36, v37, v41
	v_fma_f32 v34, -v34, v36, v35
	v_div_fmas_f32 v34, v34, v41, v36
	v_div_fixup_f32 v47, v34, v47, v57
	v_fma_f32 v34, -v52, v56, 1.0
	v_add_u32_e32 v66, 0x4000, v0
	v_fmac_f32_e32 v56, v34, v56
	v_div_scale_f32 v41, vcc, v58, v46, v58
	ds_read2_b64 v[34:37], v66 offset0:32 offset1:36
	v_mul_f32_e32 v57, v41, v56
	v_fma_f32 v53, -v52, v57, v41
	v_fmac_f32_e32 v57, v53, v56
	v_fma_f32 v41, -v52, v57, v41
	ds_read2_b64 v[52:55], v66 offset0:48 offset1:52
	v_div_fmas_f32 v41, v41, v56, v57
	v_div_fixup_f32 v46, v41, v46, v58
	ds_read2_b64 v[56:59], v66 offset0:64 offset1:68
	s_waitcnt lgkmcnt(2)
; __device__ __forceinline__ unsigned pk2(float lo, float hi) { return f2bf(lo) | (f2bf(hi) << 16); }
; __device__ __forceinline__ float bflo(unsigned u) { return __uint_as_float(u << 16); }
; __device__ __forceinline__ float bfhi(unsigned u) { return __uint_as_float(u & 0xffff0000u); }
; __device__ __forceinline__ float silu_f(float v) { return v / (1.f + __expf(-v)); }
; #define MFMA16(a, b, c) __builtin_amdgcn_mfma_f32_16x16x32_bf16(a, b, c, 0, 0, 0)
; __device__ __forceinline__ void na2_task(const Params& p_, int l, int task, unsigned char* lds) {
;     ...
; #pragma unroll
;     for (int dt = 0; dt < 4; ++dt) { f32x4 o = {0.f, 0.f, 0.f, 0.f};
; #pragma unroll
;         for (int t = 0; t < 8; ++t) { const int k0 = 2 * t, k1 = 2 * t + 1, a0 = k0 / 2, c0 = k0 % 2, a1 = k1 / 2, c1 = k1 % 2;
;             const u32x2 vlo = *(const u32x2*)(VTh + (16 * dt + fr) * 520 + a0 * 64 + kst + 16 * c0 + 4 * fq), vhi = *(const u32x2*)(VTh + (16 * dt + fr) * 520 + a1 * 64 + kst + 16 * c1 + 4 * fq);
;             o = MFMA16(mk8(vlo.x, vlo.y, vhi.x, vhi.y), mk8(pp[k0][0], pp[k0][1], pp[k1][0], pp[k1][1]), o); }
;         const u32x2 gz = *(const u32x2*)(Z + qtok * DIN + 5 * DG + h * 64 + 16 * dt + 4 * fq); u32x2 ov;
;         ov.x = pk2(o[0] * inv * silu_f(bflo(gz.x)), o[1] * inv * silu_f(bfhi(gz.x))); ov.y = pk2(o[2] * inv * silu_f(bflo(gz.y)), o[3] * inv * silu_f(bfhi(gz.y)));
;         *(u32x2*)(CAT + qtok * DM + 512 + h * 64 + 16 * dt + 4 * fq) = ov; }
	v_mfma_f32_16x16x32_bf16 v[34:37], v[34:37], v[2:5], 0
	v_mul_f32_e64 v46, v60, v46
	v_mul_f32_e64 v47, v61, v47
	ds_read2_b64 v[60:63], v66 offset0:80 offset1:84
	v_and_b32_sdwa v41, v65, v179 dst_sel:DWORD dst_unused:UNUSED_PAD src0_sel:WORD_1 src1_sel:DWORD
	s_waitcnt lgkmcnt(2)
	v_mfma_f32_16x16x32_bf16 v[34:37], v[52:55], v[6:9], v[34:37]
	v_and_b32_sdwa v52, v64, v179 dst_sel:DWORD dst_unused:UNUSED_PAD src0_sel:WORD_1 src1_sel:DWORD
	v_add3_u32 v64, v64, v52, s14
	ds_read2_b64 v[52:55], v66 offset0:96 offset1:100
	s_waitcnt lgkmcnt(2)
	v_mfma_f32_16x16x32_bf16 v[34:37], v[56:59], v[10:13], v[34:37]
	ds_read2_b64 v[56:59], v66 offset0:112 offset1:116
	v_add3_u32 v41, v65, v41, s14
	v_and_b32_sdwa v65, v47, v179 dst_sel:DWORD dst_unused:UNUSED_PAD src0_sel:WORD_1 src1_sel:DWORD
	s_waitcnt lgkmcnt(2)
	v_mfma_f32_16x16x32_bf16 v[34:37], v[60:63], v[14:17], v[34:37]
	ds_read2_b64 v[60:63], v66 offset0:128 offset1:132
	v_and_b32_sdwa v67, v46, v179 dst_sel:DWORD dst_unused:UNUSED_PAD src0_sel:WORD_1 src1_sel:DWORD
	v_add3_u32 v47, v47, v65, s14
	s_waitcnt lgkmcnt(2)
	v_mfma_f32_16x16x32_bf16 v[34:37], v[52:55], v[18:21], v[34:37]
	ds_read2_b64 v[52:55], v66 offset0:144 offset1:148
	v_add3_u32 v46, v46, v67, s14
	v_and_b32_e32 v47, 0xffff0000, v47
	s_waitcnt lgkmcnt(2)
	v_mfma_f32_16x16x32_bf16 v[34:37], v[56:59], v[22:25], v[34:37]
	v_and_b32_e32 v46, 0xffff0000, v46
	v_add_co_u32_e32 v42, vcc, s9, v42
	s_waitcnt lgkmcnt(1)
	v_mfma_f32_16x16x32_bf16 v[34:37], v[60:63], v[26:29], v[34:37]
	v_or_b32_sdwa v47, v47, v41 dst_sel:DWORD dst_unused:UNUSED_PAD src0_sel:DWORD src1_sel:WORD_1
	v_or_b32_sdwa v46, v46, v64 dst_sel:DWORD dst_unused:UNUSED_PAD src0_sel:DWORD src1_sel:WORD_1
	v_addc_co_u32_e32 v43, vcc, 0, v43, vcc
	s_waitcnt lgkmcnt(0)
	v_mfma_f32_16x16x32_bf16 v[34:37], v[52:55], v[30:33], v[34:37]
	s_waitcnt vmcnt(2)
	v_lshlrev_b32_e32 v41, 16, v49
	v_lshlrev_b32_e32 v52, 16, v48
	global_store_dwordx2 v[42:43], v[46:47], off offset:1024
	v_mul_f32_e32 v42, 0xbfb8aa3b, v52
	v_mul_f32_e32 v43, 0xbfb8aa3b, v41
	v_exp_f32_e32 v42, v42
	v_exp_f32_e32 v43, v43
	v_and_b32_e32 v58, 0xffff0000, v48
	v_mov_b32_e32 v48, v34
	v_and_b32_e32 v53, 0xffff0000, v49
	v_pk_add_f32 v[42:43], v[42:43], 1.0 op_sel_hi:[1,0]
	v_mov_b32_e32 v49, v36
	v_div_scale_f32 v47, s[12:13], v43, v43, v41
	v_rcp_f32_e32 v54, v47
	v_pk_mul_f32 v[48:49], v[40:41], v[48:49] op_sel_hi:[0,1]
	v_mul_f32_e32 v46, 0xbfb8aa3b, v58
	v_exp_f32_e32 v46, v46
	v_fma_f32 v34, -v47, v54, 1.0
	v_fmac_f32_e32 v54, v34, v54
	v_div_scale_f32 v34, vcc, v41, v43, v41
	v_mul_f32_e32 v36, v34, v54
	v_fma_f32 v55, -v47, v36, v34
	v_fmac_f32_e32 v36, v55, v54
	v_fma_f32 v34, -v47, v36, v34
	v_div_scale_f32 v47, s[12:13], v42, v42, v52
	v_rcp_f32_e32 v55, v47
	v_div_fmas_f32 v34, v34, v54, v36
	v_div_fixup_f32 v43, v34, v43, v41
	v_add_u32_e32 v64, 0x8000, v0
	v_fma_f32 v34, -v47, v55, 1.0
	v_fmac_f32_e32 v55, v34, v55
	v_div_scale_f32 v34, vcc, v52, v42, v52
	v_mul_f32_e32 v36, v34, v55
	v_fma_f32 v41, -v47, v36, v34
	v_fmac_f32_e32 v36, v41, v55
	v_mul_f32_e32 v41, 0xbfb8aa3b, v53
	v_fma_f32 v34, -v47, v36, v34
	v_exp_f32_e32 v47, v41
	v_div_fmas_f32 v34, v34, v55, v36
	v_div_fixup_f32 v42, v34, v42, v52
	v_mov_b32_e32 v36, v35
	v_pk_add_f32 v[56:57], v[46:47], 1.0 op_sel_hi:[1,0]
	v_pk_mul_f32 v[42:43], v[48:49], v[42:43]
	v_div_scale_f32 v34, s[12:13], v57, v57, v53
	v_rcp_f32_e32 v41, v34
	v_div_scale_f32 v52, s[12:13], v56, v56, v58
	v_rcp_f32_e32 v59, v52
	v_fma_f32 v35, -v34, v41, 1.0
	v_pk_mul_f32 v[60:61], v[40:41], v[36:37] op_sel_hi:[0,1]
	v_fmac_f32_e32 v41, v35, v41
	v_div_scale_f32 v35, vcc, v53, v57, v53
	v_mul_f32_e32 v36, v35, v41
	v_fma_f32 v37, -v34, v36, v35
	v_fmac_f32_e32 v36, v37, v41
	v_fma_f32 v34, -v34, v36, v35
	v_div_fmas_f32 v34, v34, v41, v36
	v_div_fixup_f32 v63, v34, v57, v53
	ds_read2_b64 v[34:37], v64 offset0:64 offset1:68
	v_fma_f32 v41, -v52, v59, 1.0
	v_fmac_f32_e32 v59, v41, v59
	v_div_scale_f32 v41, vcc, v58, v56, v58
	ds_read2_b64 v[46:49], v64 offset0:80 offset1:84
	v_mul_f32_e32 v57, v41, v59
	v_fma_f32 v53, -v52, v57, v41
	v_fmac_f32_e32 v57, v53, v59
	v_fma_f32 v41, -v52, v57, v41
	ds_read2_b64 v[52:55], v64 offset0:96 offset1:100
	s_waitcnt lgkmcnt(2)
	v_mfma_f32_16x16x32_bf16 v[34:37], v[34:37], v[2:5], 0
	v_div_fmas_f32 v41, v41, v59, v57
	v_div_fixup_f32 v62, v41, v56, v58
	ds_read2_b64 v[56:59], v64 offset0:112 offset1:116
	s_waitcnt lgkmcnt(2)
	v_mfma_f32_16x16x32_bf16 v[34:37], v[46:49], v[6:9], v[34:37]
	ds_read2_b64 v[46:49], v64 offset0:128 offset1:132
	v_pk_mul_f32 v[60:61], v[60:61], v[62:63]
	v_and_b32_sdwa v41, v43, v179 dst_sel:DWORD dst_unused:UNUSED_PAD src0_sel:WORD_1 src1_sel:DWORD
	s_waitcnt lgkmcnt(2)
	v_mfma_f32_16x16x32_bf16 v[34:37], v[52:55], v[10:13], v[34:37]
	v_and_b32_sdwa v52, v42, v179 dst_sel:DWORD dst_unused:UNUSED_PAD src0_sel:WORD_1 src1_sel:DWORD
	v_add3_u32 v42, v42, v52, s14
	ds_read2_b64 v[52:55], v64 offset0:144 offset1:148
	s_waitcnt lgkmcnt(2)
	v_mfma_f32_16x16x32_bf16 v[34:37], v[56:59], v[14:17], v[34:37]
	ds_read2_b64 v[56:59], v64 offset0:160 offset1:164
	v_add3_u32 v41, v43, v41, s14
	v_and_b32_sdwa v43, v61, v179 dst_sel:DWORD dst_unused:UNUSED_PAD src0_sel:WORD_1 src1_sel:DWORD
	s_waitcnt lgkmcnt(2)
	v_mfma_f32_16x16x32_bf16 v[34:37], v[46:49], v[18:21], v[34:37]
	v_and_b32_sdwa v62, v60, v179 dst_sel:DWORD dst_unused:UNUSED_PAD src0_sel:WORD_1 src1_sel:DWORD
	v_add3_u32 v43, v61, v43, s14
	ds_read2_b64 v[46:49], v64 offset0:176 offset1:180
	s_waitcnt lgkmcnt(2)
; __device__ __forceinline__ unsigned pk2(float lo, float hi) { return f2bf(lo) | (f2bf(hi) << 16); }
; __device__ __forceinline__ float bflo(unsigned u) { return __uint_as_float(u << 16); }
; __device__ __forceinline__ float bfhi(unsigned u) { return __uint_as_float(u & 0xffff0000u); }
; __device__ __forceinline__ float silu_f(float v) { return v / (1.f + __expf(-v)); }
; #define MFMA16(a, b, c) __builtin_amdgcn_mfma_f32_16x16x32_bf16(a, b, c, 0, 0, 0)
; __device__ __forceinline__ void na2_task(const Params& p_, int l, int task, unsigned char* lds) {
;     ...
; #pragma unroll
;     for (int dt = 0; dt < 4; ++dt) { f32x4 o = {0.f, 0.f, 0.f, 0.f};
; #pragma unroll
;         for (int t = 0; t < 8; ++t) { const int k0 = 2 * t, k1 = 2 * t + 1, a0 = k0 / 2, c0 = k0 % 2, a1 = k1 / 2, c1 = k1 % 2;
;             const u32x2 vlo = *(const u32x2*)(VTh + (16 * dt + fr) * 520 + a0 * 64 + kst + 16 * c0 + 4 * fq), vhi = *(const u32x2*)(VTh + (16 * dt + fr) * 520 + a1 * 64 + kst + 16 * c1 + 4 * fq);
;             o = MFMA16(mk8(vlo.x, vlo.y, vhi.x, vhi.y), mk8(pp[k0][0], pp[k0][1], pp[k1][0], pp[k1][1]), o); }
;         const u32x2 gz = *(const u32x2*)(Z + qtok * DIN + 5 * DG + h * 64 + 16 * dt + 4 * fq); u32x2 ov;
;         ov.x = pk2(o[0] * inv * silu_f(bflo(gz.x)), o[1] * inv * silu_f(bfhi(gz.x))); ov.y = pk2(o[2] * inv * silu_f(bflo(gz.y)), o[3] * inv * silu_f(bfhi(gz.y)));
;         *(u32x2*)(CAT + qtok * DM + 512 + h * 64 + 16 * dt + 4 * fq) = ov; }
	v_mfma_f32_16x16x32_bf16 v[34:37], v[52:55], v[22:25], v[34:37]
	v_add3_u32 v52, v60, v62, s14
	v_and_b32_e32 v43, 0xffff0000, v43
	v_and_b32_e32 v52, 0xffff0000, v52
	v_or_b32_sdwa v43, v43, v41 dst_sel:DWORD dst_unused:UNUSED_PAD src0_sel:DWORD src1_sel:WORD_1
	v_or_b32_sdwa v42, v52, v42 dst_sel:DWORD dst_unused:UNUSED_PAD src0_sel:DWORD src1_sel:WORD_1
	s_waitcnt vmcnt(2)
	v_lshlrev_b32_e32 v41, 16, v51
	v_lshlrev_b32_e32 v52, 16, v50
	global_store_dwordx2 v[38:39], v[42:43], off offset:32
	v_mul_f32_e32 v42, 0xbfb8aa3b, v52
	v_mul_f32_e32 v43, 0xbfb8aa3b, v41
	v_exp_f32_e32 v42, v42
	v_exp_f32_e32 v43, v43
	s_waitcnt lgkmcnt(1)
	v_mfma_f32_16x16x32_bf16 v[34:37], v[56:59], v[26:29], v[34:37]
	v_and_b32_e32 v56, 0xffff0000, v50
	v_and_b32_e32 v53, 0xffff0000, v51
	v_pk_add_f32 v[42:43], v[42:43], 1.0 op_sel_hi:[1,0]
	s_waitcnt lgkmcnt(0)
	v_mfma_f32_16x16x32_bf16 v[34:37], v[46:49], v[30:33], v[34:37]
	v_div_scale_f32 v47, s[12:13], v43, v43, v41
	v_rcp_f32_e32 v50, v47
	v_mul_f32_e32 v46, 0xbfb8aa3b, v56
	v_exp_f32_e32 v46, v46
	s_nop 3
	v_mov_b32_e32 v48, v34
	v_fma_f32 v34, -v47, v50, 1.0
	v_fmac_f32_e32 v50, v34, v50
	v_div_scale_f32 v34, vcc, v41, v43, v41
	v_mov_b32_e32 v49, v36
	v_mul_f32_e32 v36, v34, v50
	v_fma_f32 v51, -v47, v36, v34
	v_fmac_f32_e32 v36, v51, v50
	v_fma_f32 v34, -v47, v36, v34
	v_div_scale_f32 v47, s[12:13], v42, v42, v52
	v_rcp_f32_e32 v51, v47
	v_div_fmas_f32 v34, v34, v50, v36
	v_div_fixup_f32 v43, v34, v43, v41
	v_pk_mul_f32 v[48:49], v[40:41], v[48:49] op_sel_hi:[0,1]
	v_fma_f32 v34, -v47, v51, 1.0
	v_fmac_f32_e32 v51, v34, v51
	v_div_scale_f32 v34, vcc, v52, v42, v52
	v_mul_f32_e32 v36, v34, v51
	v_fma_f32 v41, -v47, v36, v34
	v_fmac_f32_e32 v36, v41, v51
	v_mul_f32_e32 v41, 0xbfb8aa3b, v53
	v_fma_f32 v34, -v47, v36, v34
	v_exp_f32_e32 v47, v41
	v_div_fmas_f32 v34, v34, v51, v36
	v_div_fixup_f32 v42, v34, v42, v52
	v_mov_b32_e32 v36, v35
	v_pk_add_f32 v[50:51], v[46:47], 1.0 op_sel_hi:[1,0]
	v_add_u32_e32 v0, 0xc000, v0
	v_div_scale_f32 v34, s[12:13], v51, v51, v53
	v_rcp_f32_e32 v41, v34
	v_div_scale_f32 v52, s[12:13], v50, v50, v56
	v_rcp_f32_e32 v58, v52
	v_fma_f32 v35, -v34, v41, 1.0
	v_pk_mul_f32 v[54:55], v[40:41], v[36:37] op_sel_hi:[0,1]
	v_fmac_f32_e32 v41, v35, v41
	v_div_scale_f32 v35, vcc, v53, v51, v53
	v_mul_f32_e32 v36, v35, v41
	v_fma_f32 v37, -v34, v36, v35
	v_fmac_f32_e32 v36, v37, v41
	v_fma_f32 v34, -v34, v36, v35
	v_div_fmas_f32 v34, v34, v41, v36
	v_div_fixup_f32 v57, v34, v51, v53
	ds_read2_b64 v[34:37], v0 offset0:96 offset1:100
	v_pk_mul_f32 v[42:43], v[48:49], v[42:43]
	ds_read2_b64 v[46:49], v0 offset0:112 offset1:116
	v_fma_f32 v41, -v52, v58, 1.0
	v_fmac_f32_e32 v58, v41, v58
	v_div_scale_f32 v41, vcc, v56, v50, v56
	v_mul_f32_e32 v51, v41, v58
	v_fma_f32 v53, -v52, v51, v41
	s_waitcnt lgkmcnt(1)
	v_mfma_f32_16x16x32_bf16 v[2:5], v[34:37], v[2:5], 0
	ds_read2_b64 v[34:37], v0 offset0:128 offset1:132
	v_fmac_f32_e32 v51, v53, v58
	v_fma_f32 v41, -v52, v51, v41
	v_div_fmas_f32 v41, v41, v58, v51
	v_div_fixup_f32 v56, v41, v50, v56
	ds_read2_b64 v[50:53], v0 offset0:144 offset1:148
	s_waitcnt lgkmcnt(2)
	v_mfma_f32_16x16x32_bf16 v[2:5], v[46:49], v[6:9], v[2:5]
	ds_read2_b64 v[6:9], v0 offset0:160 offset1:164
	v_pk_mul_f32 v[46:47], v[54:55], v[56:57]
	v_and_b32_sdwa v41, v43, v179 dst_sel:DWORD dst_unused:UNUSED_PAD src0_sel:WORD_1 src1_sel:DWORD
	s_waitcnt lgkmcnt(2)
	v_mfma_f32_16x16x32_bf16 v[2:5], v[34:37], v[10:13], v[2:5]
	v_and_b32_sdwa v10, v42, v179 dst_sel:DWORD dst_unused:UNUSED_PAD src0_sel:WORD_1 src1_sel:DWORD
	v_add3_u32 v34, v42, v10, s14
	ds_read2_b64 v[10:13], v0 offset0:176 offset1:180
	s_waitcnt lgkmcnt(2)
	v_mfma_f32_16x16x32_bf16 v[2:5], v[50:53], v[14:17], v[2:5]
	ds_read2_b64 v[14:17], v0 offset0:192 offset1:196
	v_and_b32_sdwa v36, v47, v179 dst_sel:DWORD dst_unused:UNUSED_PAD src0_sel:WORD_1 src1_sel:DWORD
	v_add3_u32 v35, v43, v41, s14
	s_waitcnt lgkmcnt(2)
; __device__ __forceinline__ unsigned pk2(float lo, float hi) { return f2bf(lo) | (f2bf(hi) << 16); }
; __device__ __forceinline__ float bflo(unsigned u) { return __uint_as_float(u << 16); }
; __device__ __forceinline__ float bfhi(unsigned u) { return __uint_as_float(u & 0xffff0000u); }
; __device__ __forceinline__ float silu_f(float v) { return v / (1.f + __expf(-v)); }
; #define MFMA16(a, b, c) __builtin_amdgcn_mfma_f32_16x16x32_bf16(a, b, c, 0, 0, 0)
; __device__ __forceinline__ void na2_task(const Params& p_, int l, int task, unsigned char* lds) {
;     ...
; #pragma unroll
;     for (int dt = 0; dt < 4; ++dt) { f32x4 o = {0.f, 0.f, 0.f, 0.f};
; #pragma unroll
;         for (int t = 0; t < 8; ++t) { const int k0 = 2 * t, k1 = 2 * t + 1, a0 = k0 / 2, c0 = k0 % 2, a1 = k1 / 2, c1 = k1 % 2;
;             const u32x2 vlo = *(const u32x2*)(VTh + (16 * dt + fr) * 520 + a0 * 64 + kst + 16 * c0 + 4 * fq), vhi = *(const u32x2*)(VTh + (16 * dt + fr) * 520 + a1 * 64 + kst + 16 * c1 + 4 * fq);
;             o = MFMA16(mk8(vlo.x, vlo.y, vhi.x, vhi.y), mk8(pp[k0][0], pp[k0][1], pp[k1][0], pp[k1][1]), o); }
;         const u32x2 gz = *(const u32x2*)(Z + qtok * DIN + 5 * DG + h * 64 + 16 * dt + 4 * fq); u32x2 ov;
;         ov.x = pk2(o[0] * inv * silu_f(bflo(gz.x)), o[1] * inv * silu_f(bfhi(gz.x))); ov.y = pk2(o[2] * inv * silu_f(bflo(gz.y)), o[3] * inv * silu_f(bfhi(gz.y)));
;         *(u32x2*)(CAT + qtok * DM + 512 + h * 64 + 16 * dt + 4 * fq) = ov; }
;     __syncthreads();
; __device__ __forceinline__ void ph_mixA(const Params& p, int l, unsigned char* lds) {
;     ...
;         for (int i = 0; i < nloc; ++i) { const int rq = (slot < 16) ? slot : 16 + i * 16 + (slot - 16);
;             na2_task(p, l, (xcd >> 2) * 256 + rq * 4 + (xcd & 3), lds); }
	v_mfma_f32_16x16x32_bf16 v[2:5], v[6:9], v[18:21], v[2:5]
	ds_read2_b64 v[6:9], v0 offset0:208 offset1:212
	v_and_b32_sdwa v18, v46, v179 dst_sel:DWORD dst_unused:UNUSED_PAD src0_sel:WORD_1 src1_sel:DWORD
	v_add3_u32 v19, v47, v36, s14
	s_waitcnt lgkmcnt(2)
	v_mfma_f32_16x16x32_bf16 v[2:5], v[10:13], v[22:25], v[2:5]
	v_add3_u32 v0, v46, v18, s14
	v_and_b32_e32 v10, 0xffff0000, v19
	v_and_b32_e32 v0, 0xffff0000, v0
	s_waitcnt lgkmcnt(1)
	v_mfma_f32_16x16x32_bf16 v[2:5], v[14:17], v[26:29], v[2:5]
	v_or_b32_sdwa v11, v10, v35 dst_sel:DWORD dst_unused:UNUSED_PAD src0_sel:DWORD src1_sel:WORD_1
	v_or_b32_sdwa v10, v0, v34 dst_sel:DWORD dst_unused:UNUSED_PAD src0_sel:DWORD src1_sel:WORD_1
	s_waitcnt vmcnt(2)
	v_lshlrev_b32_e32 v0, 16, v45
	v_lshlrev_b32_e32 v12, 16, v44
	s_waitcnt lgkmcnt(0)
	v_mfma_f32_16x16x32_bf16 v[2:5], v[6:9], v[30:33], v[2:5]
	v_mul_f32_e32 v6, 0xbfb8aa3b, v12
	v_mul_f32_e32 v7, 0xbfb8aa3b, v0
	v_exp_f32_e32 v6, v6
	v_exp_f32_e32 v7, v7
	global_store_dwordx2 v[38:39], v[10:11], off offset:64
	s_nop 2
	v_mov_b32_e32 v10, v2
	v_mov_b32_e32 v11, v4
	v_pk_add_f32 v[6:7], v[6:7], 1.0 op_sel_hi:[1,0]
	v_and_b32_e32 v13, 0xffff0000, v45
	v_div_scale_f32 v9, s[12:13], v7, v7, v0
	v_rcp_f32_e32 v15, v9
	v_and_b32_e32 v14, 0xffff0000, v44
	v_mul_f32_e32 v8, 0xbfb8aa3b, v14
	v_exp_f32_e32 v8, v8
	v_fma_f32 v2, -v9, v15, 1.0
	v_fmac_f32_e32 v15, v2, v15
	v_div_scale_f32 v2, vcc, v0, v7, v0
	v_mul_f32_e32 v4, v2, v15
	v_fma_f32 v16, -v9, v4, v2
	v_fmac_f32_e32 v4, v16, v15
	v_fma_f32 v2, -v9, v4, v2
	v_div_scale_f32 v9, s[12:13], v6, v6, v12
	v_rcp_f32_e32 v16, v9
	v_div_fmas_f32 v2, v2, v15, v4
	v_div_fixup_f32 v7, v2, v7, v0
	v_pk_mul_f32 v[10:11], v[40:41], v[10:11] op_sel_hi:[0,1]
	v_fma_f32 v0, -v9, v16, 1.0
	v_fmac_f32_e32 v16, v0, v16
	v_div_scale_f32 v0, vcc, v12, v6, v12
	v_mul_f32_e32 v2, v0, v16
	v_fma_f32 v4, -v9, v2, v0
	v_fmac_f32_e32 v2, v4, v16
	v_mul_f32_e32 v4, 0xbfb8aa3b, v13
	v_fma_f32 v0, -v9, v2, v0
	v_exp_f32_e32 v9, v4
	v_div_fmas_f32 v0, v0, v16, v2
	v_div_fixup_f32 v6, v0, v6, v12
	v_mov_b32_e32 v4, v3
	v_pk_add_f32 v[8:9], v[8:9], 1.0 op_sel_hi:[1,0]
	v_pk_mul_f32 v[2:3], v[40:41], v[4:5] op_sel_hi:[0,1]
	v_div_scale_f32 v0, s[12:13], v9, v9, v13
	v_rcp_f32_e32 v12, v0
	v_pk_mul_f32 v[6:7], v[10:11], v[6:7]
	s_add_i32 s9, s3, 1
	s_cmp_lt_u32 s3, 3
	v_fma_f32 v4, -v0, v12, 1.0
	v_fmac_f32_e32 v12, v4, v12
	v_div_scale_f32 v4, vcc, v13, v9, v13
	v_mul_f32_e32 v5, v4, v12
	v_fma_f32 v10, -v0, v5, v4
	v_fmac_f32_e32 v5, v10, v12
	v_fma_f32 v0, -v0, v5, v4
	v_div_scale_f32 v4, s[12:13], v8, v8, v14
	v_rcp_f32_e32 v10, v4
	v_div_fmas_f32 v0, v0, v12, v5
	v_div_fixup_f32 v5, v0, v9, v13
	s_cselect_b64 s[12:13], -1, 0
	v_fma_f32 v0, -v4, v10, 1.0
	v_fmac_f32_e32 v10, v0, v10
	v_div_scale_f32 v0, vcc, v14, v8, v14
	v_mul_f32_e32 v9, v0, v10
	v_fma_f32 v11, -v4, v9, v0
	v_fmac_f32_e32 v9, v11, v10
	v_fma_f32 v0, -v4, v9, v0
	v_div_fmas_f32 v0, v0, v10, v9
	v_div_fixup_f32 v4, v0, v8, v14
	v_pk_mul_f32 v[2:3], v[2:3], v[4:5]
	v_and_b32_sdwa v4, v6, v179 dst_sel:DWORD dst_unused:UNUSED_PAD src0_sel:WORD_1 src1_sel:DWORD
	v_add3_u32 v4, v6, v4, s14
	v_and_b32_sdwa v5, v3, v179 dst_sel:DWORD dst_unused:UNUSED_PAD src0_sel:WORD_1 src1_sel:DWORD
	v_and_b32_sdwa v6, v2, v179 dst_sel:DWORD dst_unused:UNUSED_PAD src0_sel:WORD_1 src1_sel:DWORD
	v_and_b32_sdwa v0, v7, v179 dst_sel:DWORD dst_unused:UNUSED_PAD src0_sel:WORD_1 src1_sel:DWORD
	v_add3_u32 v3, v3, v5, s14
	v_add3_u32 v2, v2, v6, s14
	v_add3_u32 v0, v7, v0, s14
	v_and_b32_e32 v3, 0xffff0000, v3
	v_and_b32_e32 v2, 0xffff0000, v2
	s_and_b64 s[12:13], s[56:57], s[12:13]
	v_or_b32_sdwa v3, v3, v0 dst_sel:DWORD dst_unused:UNUSED_PAD src0_sel:DWORD src1_sel:WORD_1
	v_or_b32_sdwa v2, v2, v4 dst_sel:DWORD dst_unused:UNUSED_PAD src0_sel:DWORD src1_sel:WORD_1
	s_andn2_b64 vcc, exec, s[12:13]
	s_mov_b32 s3, s9
	global_store_dwordx2 v[38:39], v[2:3], off offset:96
	s_barrier
	s_cbranch_vccnz .LBB0_394
